# speedup vs baseline: 1.0314x; 1.0003x over previous
;     __device__ __forceinline__ bf16_t* H() const { return (bf16_t*)(ws + OFF_H); }
;     __device__ __forceinline__ bf16_t* VbT() const { return (bf16_t*)(ws + OFF_VbT); }
;     __device__ __forceinline__ bf16_t* VsbT() const { return (bf16_t*)(ws + OFF_VsbT); }
; DEV bf16_t f2bf(float f) { return (bf16_t)(pk_bf16(f, 0.f) & 0xffffu); }
; template <int H>
; DEV void epi1_group(const Params& p, int l, bool samp, int rbase, int g64, int fq, int fr, char* wsm, const f32x4 (&acc)[4][8]) {
;     ...
;         const int head = g64 - 38;
; #pragma unroll
;         for (int mi = 0; mi < 4; ++mi) {
;             const int row = rbase + mi * 16;
; #pragma unroll
;             for (int ni = 0; ni < 4; ++ni) {
;                 const f32x4 v = acc[mi][H * 4 + ni]; const int d = ni * 16 + cl, c = head * 64 + d;
;                 if (!samp) {
;                     *(f32x4*)(p.out + O_SV_P + ((size_t)l * SEQ + row) * 256 + c) = v;
; #pragma unroll
;                     for (int j = 0; j < 4; ++j) p.VbT()[(size_t)(head * 64 + d + j) * SEQ + row] = f2bf(v[j]);
;                 } else {
;                     const int s = row - SEQ, b = s >> 4, tt = s & 15;
;                     *(f32x4*)(p.out + O_SV_S + ((size_t)l * NSMP + s) * 256 + c) = v;
; #pragma unroll
;                     for (int j = 0; j < 4; ++j) p.VsbT()[((size_t)(b * 4 + head) * 64 + d + j) * KSP + PAST + tt] = f2bf(v[j]);
;                 }
.LBB0_1950:
	s_andn2_saveexec_b64 s[22:23], s[40:41]
	s_cbranch_execz .LBB0_2015
	v_subrev_u32_e32 v184, 38, v206
	v_lshlrev_b32_e32 v144, 6, v184
	v_ashrrev_i32_e32 v149, 31, v148
	v_lshlrev_b64 v[132:133], 10, v[148:149]
	v_or_b32_e32 v32, v144, v147
	v_cndmask_b32_e64 v134, 0, 1, s[42:43]
	v_cvt_pk_bf16_f32 v131, v126, s0
	v_cvt_pk_bf16_f32 v130, v128, s0
	s_mov_b64 s[28:29], -1
	v_cmp_ne_u32_e64 s[40:41], 1, v134
	s_andn2_b64 vcc, exec, s[42:43]
	v_lshl_add_u64 v[170:171], s[46:47], 0, v[132:133]
	v_lshlrev_b64 v[164:165], 15, v[32:33]
	v_lshl_add_u64 v[168:169], v[148:149], 1, s[8:9]
	v_or_b32_e32 v142, 1, v32
	v_or_b32_e32 v136, 2, v32
	v_or_b32_e32 v132, 3, v32
	s_cbranch_vccnz .LBB0_1953
	v_lshl_add_u64 v[134:135], v[32:33], 2, v[170:171]
	flat_store_dwordx4 v[134:135], v[126:129]
	v_lshl_add_u64 v[134:135], v[168:169], 0, v[164:165]
	v_mov_b32_e32 v143, v33
	v_lshrrev_b32_e32 v226, 6, v186
	v_mul_u32_u24_e32 v226, 0x4400, v226
	v_bfe_u32 v227, v186, 4, 2
	v_mul_u32_u24_e32 v230, 0x240, v227
	v_add_u32_e32 v226, v226, v230
	v_and_b32_e32 v230, 15, v186
	v_lshl_add_u32 v226, v230, 1, v226
	v_mov_b32_e32 v228, v134
	v_mov_b32_e32 v229, v135
	v_and_b32_e32 v231, 7, v230
	v_lshlrev_b32_e32 v231, 4, v231
	v_lshlrev_b32_e32 v234, 1, v230
	v_sub_u32_e32 v231, v231, v234
	v_lshrrev_b32_e32 v234, 3, v230
	v_lshl_add_u32 v231, v234, 15, v231
	v_lshlrev_b32_e32 v234, 16, v227
	v_sub_u32_e32 v234, v231, v234
	v_ashrrev_i32_e32 v235, 31, v234
	v_lshl_add_u64 v[228:229], v[228:229], 0, v[234:235]
	v_mov_b32_e32 v232, 0x40000
	v_mov_b32_e32 v233, 0
	ds_write_b16 v226, v131 offset:0
	v_lshlrev_b64 v[134:135], 15, v[142:143]
	v_cvt_pk_bf16_f32 v133, v127, s0
	v_lshl_add_u64 v[134:135], v[168:169], 0, v[134:135]
	v_mov_b32_e32 v137, v33
	ds_write_b16 v226, v133 offset:144
	v_lshlrev_b64 v[134:135], 15, v[136:137]
	v_lshl_add_u64 v[134:135], v[168:169], 0, v[134:135]
	v_mov_b32_e32 v133, v33
	ds_write_b16 v226, v130 offset:288
	v_lshlrev_b64 v[134:135], 15, v[132:133]
	v_cvt_pk_bf16_f32 v137, v129, s0
	v_lshl_add_u64 v[134:135], v[168:169], 0, v[134:135]
	s_mov_b64 s[28:29], 0
	ds_write_b16 v226, v137 offset:432

;     __device__ __forceinline__ bf16_t* H() const { return (bf16_t*)(ws + OFF_H); }
;     __device__ __forceinline__ bf16_t* VbT() const { return (bf16_t*)(ws + OFF_VbT); }
;     __device__ __forceinline__ bf16_t* VsbT() const { return (bf16_t*)(ws + OFF_VsbT); }
; DEV bf16_t f2bf(float f) { return (bf16_t)(pk_bf16(f, 0.f) & 0xffffu); }
; template <int H>
; DEV void epi1_group(const Params& p, int l, bool samp, int rbase, int g64, int fq, int fr, char* wsm, const f32x4 (&acc)[4][8]) {
;     ...
;         const int head = g64 - 38;
; #pragma unroll
;         for (int mi = 0; mi < 4; ++mi) {
;             const int row = rbase + mi * 16;
; #pragma unroll
;             for (int ni = 0; ni < 4; ++ni) {
;                 const f32x4 v = acc[mi][H * 4 + ni]; const int d = ni * 16 + cl, c = head * 64 + d;
;                 if (!samp) {
;                     *(f32x4*)(p.out + O_SV_P + ((size_t)l * SEQ + row) * 256 + c) = v;
; #pragma unroll
;                     for (int j = 0; j < 4; ++j) p.VbT()[(size_t)(head * 64 + d + j) * SEQ + row] = f2bf(v[j]);
;                 } else {
;                     const int s = row - SEQ, b = s >> 4, tt = s & 15;
;                     *(f32x4*)(p.out + O_SV_S + ((size_t)l * NSMP + s) * 256 + c) = v;
; #pragma unroll
;                     for (int j = 0; j < 4; ++j) p.VsbT()[((size_t)(b * 4 + head) * 64 + d + j) * KSP + PAST + tt] = f2bf(v[j]);
;                 }
.LBB0_1955:
	v_or_b32_e32 v149, 16, v147
	v_or_b32_e32 v134, v144, v149
	v_mov_b32_e32 v135, v33
	v_cvt_pk_bf16_f32 v137, v122, s0
	v_cvt_pk_bf16_f32 v133, v124, s0
	s_mov_b64 s[28:29], -1
	s_and_b64 vcc, exec, s[40:41]
	v_add_u32_e32 v130, v144, v147
	v_lshlrev_b64 v[166:167], 15, v[134:135]
	v_or_b32_e32 v152, 1, v134
	v_or_b32_e32 v140, 2, v134
	v_or_b32_e32 v134, 3, v134
	s_cbranch_vccnz .LBB0_1957
	v_mov_b32_e32 v131, v33
	v_lshl_add_u64 v[138:139], v[130:131], 2, v[170:171]
	flat_store_dwordx4 v[138:139], v[122:125] offset:64
	v_lshl_add_u64 v[138:139], v[168:169], 0, v[166:167]
	v_mov_b32_e32 v153, v33
	ds_write_b16 v226, v137 offset:2304
	v_lshlrev_b64 v[138:139], 15, v[152:153]
	v_cvt_pk_bf16_f32 v131, v123, s0
	v_lshl_add_u64 v[138:139], v[168:169], 0, v[138:139]
	v_mov_b32_e32 v141, v33
	ds_write_b16 v226, v131 offset:2448
	v_lshlrev_b64 v[138:139], 15, v[140:141]
	v_lshl_add_u64 v[138:139], v[168:169], 0, v[138:139]
	v_mov_b32_e32 v135, v33
	ds_write_b16 v226, v133 offset:2592
	v_lshlrev_b64 v[138:139], 15, v[134:135]
	v_cvt_pk_bf16_f32 v131, v125, s0
	v_lshl_add_u64 v[138:139], v[168:169], 0, v[138:139]
	s_mov_b64 s[28:29], 0
	ds_write_b16 v226, v131 offset:2736

;     __device__ __forceinline__ bf16_t* H() const { return (bf16_t*)(ws + OFF_H); }
;     __device__ __forceinline__ bf16_t* VbT() const { return (bf16_t*)(ws + OFF_VbT); }
;     __device__ __forceinline__ bf16_t* VsbT() const { return (bf16_t*)(ws + OFF_VsbT); }
; DEV bf16_t f2bf(float f) { return (bf16_t)(pk_bf16(f, 0.f) & 0xffffu); }
; template <int H>
; DEV void epi1_group(const Params& p, int l, bool samp, int rbase, int g64, int fq, int fr, char* wsm, const f32x4 (&acc)[4][8]) {
;     ...
;         const int head = g64 - 38;
; #pragma unroll
;         for (int mi = 0; mi < 4; ++mi) {
;             const int row = rbase + mi * 16;
; #pragma unroll
;             for (int ni = 0; ni < 4; ++ni) {
;                 const f32x4 v = acc[mi][H * 4 + ni]; const int d = ni * 16 + cl, c = head * 64 + d;
;                 if (!samp) {
;                     *(f32x4*)(p.out + O_SV_P + ((size_t)l * SEQ + row) * 256 + c) = v;
; #pragma unroll
;                     for (int j = 0; j < 4; ++j) p.VbT()[(size_t)(head * 64 + d + j) * SEQ + row] = f2bf(v[j]);
;                 } else {
;                     const int s = row - SEQ, b = s >> 4, tt = s & 15;
;                     *(f32x4*)(p.out + O_SV_S + ((size_t)l * NSMP + s) * 256 + c) = v;
; #pragma unroll
;                     for (int j = 0; j < 4; ++j) p.VsbT()[((size_t)(b * 4 + head) * 64 + d + j) * KSP + PAST + tt] = f2bf(v[j]);
;                 }
.LBB0_1959:
	v_or_b32_e32 v185, 32, v147
	v_or_b32_e32 v138, v144, v185
	v_mov_b32_e32 v139, v33
	v_cvt_pk_bf16_f32 v135, v118, s0
	v_cvt_pk_bf16_f32 v133, v120, s0
	s_mov_b64 s[28:29], -1
	s_and_b64 vcc, exec, s[40:41]
	v_lshlrev_b64 v[172:173], 15, v[138:139]
	v_or_b32_e32 v160, 1, v138
	v_or_b32_e32 v150, 2, v138
	v_or_b32_e32 v138, 3, v138
	s_cbranch_vccnz .LBB0_1961
	v_mov_b32_e32 v131, v33
	v_lshl_add_u64 v[158:159], v[130:131], 2, v[170:171]
	flat_store_dwordx4 v[158:159], v[118:121] offset:128
	v_lshl_add_u64 v[158:159], v[168:169], 0, v[172:173]
	v_mov_b32_e32 v161, v33
	ds_write_b16 v226, v135 offset:4608
	v_lshlrev_b64 v[158:159], 15, v[160:161]
	v_cvt_pk_bf16_f32 v131, v119, s0
	v_lshl_add_u64 v[158:159], v[168:169], 0, v[158:159]
	v_mov_b32_e32 v151, v33
	ds_write_b16 v226, v131 offset:4752
	v_lshlrev_b64 v[158:159], 15, v[150:151]
	v_lshl_add_u64 v[158:159], v[168:169], 0, v[158:159]
	v_mov_b32_e32 v139, v33
	ds_write_b16 v226, v133 offset:4896
	v_lshlrev_b64 v[158:159], 15, v[138:139]
	v_cvt_pk_bf16_f32 v131, v121, s0
	v_lshl_add_u64 v[158:159], v[168:169], 0, v[158:159]
	s_mov_b64 s[28:29], 0
	ds_write_b16 v226, v131 offset:5040

;     __device__ __forceinline__ bf16_t* H() const { return (bf16_t*)(ws + OFF_H); }
;     __device__ __forceinline__ bf16_t* VbT() const { return (bf16_t*)(ws + OFF_VbT); }
;     __device__ __forceinline__ bf16_t* VsbT() const { return (bf16_t*)(ws + OFF_VsbT); }
; DEV bf16_t f2bf(float f) { return (bf16_t)(pk_bf16(f, 0.f) & 0xffffu); }
; template <int H>
; DEV void epi1_group(const Params& p, int l, bool samp, int rbase, int g64, int fq, int fr, char* wsm, const f32x4 (&acc)[4][8]) {
;     ...
;         const int head = g64 - 38;
; #pragma unroll
;         for (int mi = 0; mi < 4; ++mi) {
;             const int row = rbase + mi * 16;
; #pragma unroll
;             for (int ni = 0; ni < 4; ++ni) {
;                 const f32x4 v = acc[mi][H * 4 + ni]; const int d = ni * 16 + cl, c = head * 64 + d;
;                 if (!samp) {
;                     *(f32x4*)(p.out + O_SV_P + ((size_t)l * SEQ + row) * 256 + c) = v;
; #pragma unroll
;                     for (int j = 0; j < 4; ++j) p.VbT()[(size_t)(head * 64 + d + j) * SEQ + row] = f2bf(v[j]);
;                 } else {
;                     const int s = row - SEQ, b = s >> 4, tt = s & 15;
;                     *(f32x4*)(p.out + O_SV_S + ((size_t)l * NSMP + s) * 256 + c) = v;
; #pragma unroll
;                     for (int j = 0; j < 4; ++j) p.VsbT()[((size_t)(b * 4 + head) * 64 + d + j) * KSP + PAST + tt] = f2bf(v[j]);
;                 }
.LBB0_1963:
	v_or_b32_e32 v207, 48, v147
	v_or_b32_e32 v144, v144, v207
	v_mov_b32_e32 v145, v33
	v_cvt_pk_bf16_f32 v135, v114, s0
	v_cvt_pk_bf16_f32 v133, v116, s0
	s_mov_b64 s[28:29], -1
	s_and_b64 vcc, exec, s[40:41]
	v_lshlrev_b64 v[174:175], 15, v[144:145]
	v_or_b32_e32 v162, 1, v144
	v_or_b32_e32 v158, 2, v144
	v_or_b32_e32 v144, 3, v144
	s_cbranch_vccnz .LBB0_1965
	v_mov_b32_e32 v131, v33
	v_lshl_add_u64 v[170:171], v[130:131], 2, v[170:171]
	flat_store_dwordx4 v[170:171], v[114:117] offset:192
	v_lshl_add_u64 v[170:171], v[168:169], 0, v[174:175]
	v_mov_b32_e32 v163, v33
	ds_write_b16 v226, v135 offset:6912
	v_lshlrev_b64 v[170:171], 15, v[162:163]
	v_cvt_pk_bf16_f32 v131, v115, s0
	v_lshl_add_u64 v[170:171], v[168:169], 0, v[170:171]
	v_mov_b32_e32 v159, v33
	ds_write_b16 v226, v131 offset:7056
	v_lshlrev_b64 v[170:171], 15, v[158:159]
	v_lshl_add_u64 v[170:171], v[168:169], 0, v[170:171]
	v_mov_b32_e32 v145, v33
	ds_write_b16 v226, v133 offset:7200
	v_lshlrev_b64 v[170:171], 15, v[144:145]
	v_cvt_pk_bf16_f32 v131, v117, s0
	v_lshl_add_u64 v[168:169], v[168:169], 0, v[170:171]
	s_mov_b64 s[28:29], 0
	ds_write_b16 v226, v131 offset:7344

;     __device__ __forceinline__ bf16_t* H() const { return (bf16_t*)(ws + OFF_H); }
;     __device__ __forceinline__ bf16_t* VbT() const { return (bf16_t*)(ws + OFF_VbT); }
;     __device__ __forceinline__ bf16_t* VsbT() const { return (bf16_t*)(ws + OFF_VsbT); }
; DEV bf16_t f2bf(float f) { return (bf16_t)(pk_bf16(f, 0.f) & 0xffffu); }
; template <int H>
; DEV void epi1_group(const Params& p, int l, bool samp, int rbase, int g64, int fq, int fr, char* wsm, const f32x4 (&acc)[4][8]) {
;     ...
;         const int head = g64 - 38;
; #pragma unroll
;         for (int mi = 0; mi < 4; ++mi) {
;             const int row = rbase + mi * 16;
; #pragma unroll
;             for (int ni = 0; ni < 4; ++ni) {
;                 const f32x4 v = acc[mi][H * 4 + ni]; const int d = ni * 16 + cl, c = head * 64 + d;
;                 if (!samp) {
;                     *(f32x4*)(p.out + O_SV_P + ((size_t)l * SEQ + row) * 256 + c) = v;
; #pragma unroll
;                     for (int j = 0; j < 4; ++j) p.VbT()[(size_t)(head * 64 + d + j) * SEQ + row] = f2bf(v[j]);
;                 } else {
;                     const int s = row - SEQ, b = s >> 4, tt = s & 15;
;                     *(f32x4*)(p.out + O_SV_S + ((size_t)l * NSMP + s) * 256 + c) = v;
; #pragma unroll
;                     for (int j = 0; j < 4; ++j) p.VsbT()[((size_t)(b * 4 + head) * 64 + d + j) * KSP + PAST + tt] = f2bf(v[j]);
;                 }
.LBB0_1967:
	v_or_b32_e32 v168, 16, v148
	v_ashrrev_i32_e32 v169, 31, v168
	v_lshlrev_b64 v[170:171], 10, v[168:169]
	v_cvt_pk_bf16_f32 v135, v110, s0
	v_cvt_pk_bf16_f32 v131, v112, s0
	s_mov_b64 s[28:29], -1
	s_and_b64 vcc, exec, s[40:41]
	v_lshl_add_u64 v[180:181], s[46:47], 0, v[170:171]
	v_lshlrev_b64 v[176:177], 1, v[168:169]
	v_lshl_add_u64 v[170:171], s[8:9], 0, v[164:165]
	s_cbranch_vccnz .LBB0_1969
	v_lshl_add_u64 v[164:165], v[32:33], 2, v[180:181]
	flat_store_dwordx4 v[164:165], v[110:113]
	v_lshl_add_u64 v[164:165], v[170:171], 0, v[176:177]
	v_mov_b32_e32 v143, v33
	ds_write_b16 v226, v135 offset:32
	v_lshlrev_b64 v[164:165], 15, v[142:143]
	v_lshl_add_u64 v[164:165], s[8:9], 0, v[164:165]
	v_cvt_pk_bf16_f32 v133, v111, s0
	v_lshl_add_u64 v[164:165], v[164:165], 0, v[176:177]
	v_mov_b32_e32 v137, v33
	ds_write_b16 v226, v133 offset:176
	v_lshlrev_b64 v[164:165], 15, v[136:137]
	v_lshl_add_u64 v[164:165], s[8:9], 0, v[164:165]
	v_lshl_add_u64 v[164:165], v[164:165], 0, v[176:177]
	v_mov_b32_e32 v133, v33
	ds_write_b16 v226, v131 offset:320
	v_lshlrev_b64 v[164:165], 15, v[132:133]
	v_lshl_add_u64 v[164:165], s[8:9], 0, v[164:165]
	v_cvt_pk_bf16_f32 v137, v113, s0
	v_lshl_add_u64 v[164:165], v[164:165], 0, v[176:177]
	s_mov_b64 s[28:29], 0
	ds_write_b16 v226, v137 offset:464

;     __device__ __forceinline__ bf16_t* H() const { return (bf16_t*)(ws + OFF_H); }
;     __device__ __forceinline__ bf16_t* VbT() const { return (bf16_t*)(ws + OFF_VbT); }
;     __device__ __forceinline__ bf16_t* VsbT() const { return (bf16_t*)(ws + OFF_VsbT); }
; DEV bf16_t f2bf(float f) { return (bf16_t)(pk_bf16(f, 0.f) & 0xffffu); }
; template <int H>
; DEV void epi1_group(const Params& p, int l, bool samp, int rbase, int g64, int fq, int fr, char* wsm, const f32x4 (&acc)[4][8]) {
;     ...
;         const int head = g64 - 38;
; #pragma unroll
;         for (int mi = 0; mi < 4; ++mi) {
;             const int row = rbase + mi * 16;
; #pragma unroll
;             for (int ni = 0; ni < 4; ++ni) {
;                 const f32x4 v = acc[mi][H * 4 + ni]; const int d = ni * 16 + cl, c = head * 64 + d;
;                 if (!samp) {
;                     *(f32x4*)(p.out + O_SV_P + ((size_t)l * SEQ + row) * 256 + c) = v;
; #pragma unroll
;                     for (int j = 0; j < 4; ++j) p.VbT()[(size_t)(head * 64 + d + j) * SEQ + row] = f2bf(v[j]);
;                 } else {
;                     const int s = row - SEQ, b = s >> 4, tt = s & 15;
;                     *(f32x4*)(p.out + O_SV_S + ((size_t)l * NSMP + s) * 256 + c) = v;
; #pragma unroll
;                     for (int j = 0; j < 4; ++j) p.VsbT()[((size_t)(b * 4 + head) * 64 + d + j) * KSP + PAST + tt] = f2bf(v[j]);
;                 }
.LBB0_1971:
	v_cvt_pk_bf16_f32 v137, v106, s0
	v_cvt_pk_bf16_f32 v133, v108, s0
	s_mov_b64 s[28:29], -1
	s_and_b64 vcc, exec, s[40:41]
	v_lshl_add_u64 v[168:169], s[8:9], 0, v[166:167]
	s_cbranch_vccnz .LBB0_1973
	v_mov_b32_e32 v131, v33
	v_lshl_add_u64 v[164:165], v[130:131], 2, v[180:181]
	flat_store_dwordx4 v[164:165], v[106:109] offset:64
	v_lshl_add_u64 v[164:165], v[168:169], 0, v[176:177]
	v_mov_b32_e32 v153, v33
	ds_write_b16 v226, v137 offset:2336
	v_lshlrev_b64 v[164:165], 15, v[152:153]
	v_lshl_add_u64 v[164:165], s[8:9], 0, v[164:165]
	v_cvt_pk_bf16_f32 v131, v107, s0
	v_lshl_add_u64 v[164:165], v[164:165], 0, v[176:177]
	v_mov_b32_e32 v141, v33
	ds_write_b16 v226, v131 offset:2480
	v_lshlrev_b64 v[164:165], 15, v[140:141]
	v_lshl_add_u64 v[164:165], s[8:9], 0, v[164:165]
	v_lshl_add_u64 v[164:165], v[164:165], 0, v[176:177]
	v_mov_b32_e32 v135, v33
	ds_write_b16 v226, v133 offset:2624
	v_lshlrev_b64 v[164:165], 15, v[134:135]
	v_lshl_add_u64 v[164:165], s[8:9], 0, v[164:165]
	v_cvt_pk_bf16_f32 v131, v109, s0
	v_lshl_add_u64 v[164:165], v[164:165], 0, v[176:177]
	s_mov_b64 s[28:29], 0
	ds_write_b16 v226, v131 offset:2768

;     __device__ __forceinline__ bf16_t* H() const { return (bf16_t*)(ws + OFF_H); }
;     __device__ __forceinline__ bf16_t* VbT() const { return (bf16_t*)(ws + OFF_VbT); }
;     __device__ __forceinline__ bf16_t* VsbT() const { return (bf16_t*)(ws + OFF_VsbT); }
; DEV bf16_t f2bf(float f) { return (bf16_t)(pk_bf16(f, 0.f) & 0xffffu); }
; template <int H>
; DEV void epi1_group(const Params& p, int l, bool samp, int rbase, int g64, int fq, int fr, char* wsm, const f32x4 (&acc)[4][8]) {
;     ...
;         const int head = g64 - 38;
; #pragma unroll
;         for (int mi = 0; mi < 4; ++mi) {
;             const int row = rbase + mi * 16;
; #pragma unroll
;             for (int ni = 0; ni < 4; ++ni) {
;                 const f32x4 v = acc[mi][H * 4 + ni]; const int d = ni * 16 + cl, c = head * 64 + d;
;                 if (!samp) {
;                     *(f32x4*)(p.out + O_SV_P + ((size_t)l * SEQ + row) * 256 + c) = v;
; #pragma unroll
;                     for (int j = 0; j < 4; ++j) p.VbT()[(size_t)(head * 64 + d + j) * SEQ + row] = f2bf(v[j]);
;                 } else {
;                     const int s = row - SEQ, b = s >> 4, tt = s & 15;
;                     *(f32x4*)(p.out + O_SV_S + ((size_t)l * NSMP + s) * 256 + c) = v;
; #pragma unroll
;                     for (int j = 0; j < 4; ++j) p.VsbT()[((size_t)(b * 4 + head) * 64 + d + j) * KSP + PAST + tt] = f2bf(v[j]);
;                 }
.LBB0_1975:
	v_cvt_pk_bf16_f32 v135, v102, s0
	v_cvt_pk_bf16_f32 v133, v104, s0
	s_mov_b64 s[28:29], -1
	s_and_b64 vcc, exec, s[40:41]
	v_lshl_add_u64 v[166:167], s[8:9], 0, v[172:173]
	s_cbranch_vccnz .LBB0_1977
	v_mov_b32_e32 v131, v33
	v_lshl_add_u64 v[164:165], v[130:131], 2, v[180:181]
	flat_store_dwordx4 v[164:165], v[102:105] offset:128
	v_lshl_add_u64 v[164:165], v[166:167], 0, v[176:177]
	v_mov_b32_e32 v161, v33
	ds_write_b16 v226, v135 offset:4640
	v_lshlrev_b64 v[164:165], 15, v[160:161]
	v_lshl_add_u64 v[164:165], s[8:9], 0, v[164:165]
	v_cvt_pk_bf16_f32 v131, v103, s0
	v_lshl_add_u64 v[164:165], v[164:165], 0, v[176:177]
	v_mov_b32_e32 v151, v33
	ds_write_b16 v226, v131 offset:4784
	v_lshlrev_b64 v[164:165], 15, v[150:151]
	v_lshl_add_u64 v[164:165], s[8:9], 0, v[164:165]
	v_lshl_add_u64 v[164:165], v[164:165], 0, v[176:177]
	v_mov_b32_e32 v139, v33
	ds_write_b16 v226, v133 offset:4928
	v_lshlrev_b64 v[164:165], 15, v[138:139]
	v_lshl_add_u64 v[164:165], s[8:9], 0, v[164:165]
	v_cvt_pk_bf16_f32 v131, v105, s0
	v_lshl_add_u64 v[164:165], v[164:165], 0, v[176:177]
	s_mov_b64 s[28:29], 0
	ds_write_b16 v226, v131 offset:5072

;     __device__ __forceinline__ bf16_t* H() const { return (bf16_t*)(ws + OFF_H); }
;     __device__ __forceinline__ bf16_t* VbT() const { return (bf16_t*)(ws + OFF_VbT); }
;     __device__ __forceinline__ bf16_t* VsbT() const { return (bf16_t*)(ws + OFF_VsbT); }
; DEV bf16_t f2bf(float f) { return (bf16_t)(pk_bf16(f, 0.f) & 0xffffu); }
; template <int H>
; DEV void epi1_group(const Params& p, int l, bool samp, int rbase, int g64, int fq, int fr, char* wsm, const f32x4 (&acc)[4][8]) {
;     ...
;         const int head = g64 - 38;
; #pragma unroll
;         for (int mi = 0; mi < 4; ++mi) {
;             const int row = rbase + mi * 16;
; #pragma unroll
;             for (int ni = 0; ni < 4; ++ni) {
;                 const f32x4 v = acc[mi][H * 4 + ni]; const int d = ni * 16 + cl, c = head * 64 + d;
;                 if (!samp) {
;                     *(f32x4*)(p.out + O_SV_P + ((size_t)l * SEQ + row) * 256 + c) = v;
; #pragma unroll
;                     for (int j = 0; j < 4; ++j) p.VbT()[(size_t)(head * 64 + d + j) * SEQ + row] = f2bf(v[j]);
;                 } else {
;                     const int s = row - SEQ, b = s >> 4, tt = s & 15;
;                     *(f32x4*)(p.out + O_SV_S + ((size_t)l * NSMP + s) * 256 + c) = v;
; #pragma unroll
;                     for (int j = 0; j < 4; ++j) p.VsbT()[((size_t)(b * 4 + head) * 64 + d + j) * KSP + PAST + tt] = f2bf(v[j]);
;                 }
.LBB0_1979:
	v_cvt_pk_bf16_f32 v135, v98, s0
	v_cvt_pk_bf16_f32 v133, v100, s0
	s_mov_b64 s[28:29], -1
	s_and_b64 vcc, exec, s[40:41]
	v_lshl_add_u64 v[164:165], s[8:9], 0, v[174:175]
	s_cbranch_vccnz .LBB0_1981
	v_mov_b32_e32 v131, v33
	v_lshl_add_u64 v[172:173], v[130:131], 2, v[180:181]
	flat_store_dwordx4 v[172:173], v[98:101] offset:192
	v_lshl_add_u64 v[172:173], v[164:165], 0, v[176:177]
	v_mov_b32_e32 v163, v33
	ds_write_b16 v226, v135 offset:6944
	v_lshlrev_b64 v[172:173], 15, v[162:163]
	v_lshl_add_u64 v[172:173], s[8:9], 0, v[172:173]
	v_cvt_pk_bf16_f32 v131, v99, s0
	v_lshl_add_u64 v[172:173], v[172:173], 0, v[176:177]
	v_mov_b32_e32 v159, v33
	ds_write_b16 v226, v131 offset:7088
	v_lshlrev_b64 v[172:173], 15, v[158:159]
	v_lshl_add_u64 v[172:173], s[8:9], 0, v[172:173]
	v_lshl_add_u64 v[172:173], v[172:173], 0, v[176:177]
	v_mov_b32_e32 v145, v33
	ds_write_b16 v226, v133 offset:7232
	v_lshlrev_b64 v[172:173], 15, v[144:145]
	v_lshl_add_u64 v[172:173], s[8:9], 0, v[172:173]
	v_cvt_pk_bf16_f32 v131, v101, s0
	v_lshl_add_u64 v[172:173], v[172:173], 0, v[176:177]
	s_mov_b64 s[28:29], 0
	ds_write_b16 v226, v131 offset:7376

;     __device__ __forceinline__ bf16_t* H() const { return (bf16_t*)(ws + OFF_H); }
;     __device__ __forceinline__ bf16_t* VbT() const { return (bf16_t*)(ws + OFF_VbT); }
;     __device__ __forceinline__ bf16_t* VsbT() const { return (bf16_t*)(ws + OFF_VsbT); }
; DEV bf16_t f2bf(float f) { return (bf16_t)(pk_bf16(f, 0.f) & 0xffffu); }
; template <int H>
; DEV void epi1_group(const Params& p, int l, bool samp, int rbase, int g64, int fq, int fr, char* wsm, const f32x4 (&acc)[4][8]) {
;     ...
;         const int head = g64 - 38;
; #pragma unroll
;         for (int mi = 0; mi < 4; ++mi) {
;             const int row = rbase + mi * 16;
; #pragma unroll
;             for (int ni = 0; ni < 4; ++ni) {
;                 const f32x4 v = acc[mi][H * 4 + ni]; const int d = ni * 16 + cl, c = head * 64 + d;
;                 if (!samp) {
;                     *(f32x4*)(p.out + O_SV_P + ((size_t)l * SEQ + row) * 256 + c) = v;
; #pragma unroll
;                     for (int j = 0; j < 4; ++j) p.VbT()[(size_t)(head * 64 + d + j) * SEQ + row] = f2bf(v[j]);
;                 } else {
;                     const int s = row - SEQ, b = s >> 4, tt = s & 15;
;                     *(f32x4*)(p.out + O_SV_S + ((size_t)l * NSMP + s) * 256 + c) = v;
; #pragma unroll
;                     for (int j = 0; j < 4; ++j) p.VsbT()[((size_t)(b * 4 + head) * 64 + d + j) * KSP + PAST + tt] = f2bf(v[j]);
;                 }
.LBB0_1983:
	v_or_b32_e32 v172, 32, v148
	v_ashrrev_i32_e32 v173, 31, v172
	v_lshlrev_b64 v[174:175], 10, v[172:173]
	v_cvt_pk_bf16_f32 v135, v94, s0
	v_cvt_pk_bf16_f32 v131, v96, s0
	s_mov_b64 s[28:29], -1
	s_and_b64 vcc, exec, s[40:41]
	v_lshl_add_u64 v[176:177], s[46:47], 0, v[174:175]
	v_lshlrev_b64 v[172:173], 1, v[172:173]
	s_cbranch_vccnz .LBB0_1985
	v_lshl_add_u64 v[174:175], v[32:33], 2, v[176:177]
	flat_store_dwordx4 v[174:175], v[94:97]
	v_lshl_add_u64 v[174:175], v[170:171], 0, v[172:173]
	v_mov_b32_e32 v143, v33
	ds_write_b16 v226, v135 offset:64
	v_lshlrev_b64 v[174:175], 15, v[142:143]
	v_lshl_add_u64 v[174:175], s[8:9], 0, v[174:175]
	v_cvt_pk_bf16_f32 v133, v95, s0
	v_lshl_add_u64 v[174:175], v[174:175], 0, v[172:173]
	v_mov_b32_e32 v137, v33
	ds_write_b16 v226, v133 offset:208
	v_lshlrev_b64 v[174:175], 15, v[136:137]
	v_lshl_add_u64 v[174:175], s[8:9], 0, v[174:175]
	v_lshl_add_u64 v[174:175], v[174:175], 0, v[172:173]
	v_mov_b32_e32 v133, v33
	ds_write_b16 v226, v131 offset:352
	v_lshlrev_b64 v[174:175], 15, v[132:133]
	v_lshl_add_u64 v[174:175], s[8:9], 0, v[174:175]
	v_cvt_pk_bf16_f32 v137, v97, s0
	v_lshl_add_u64 v[174:175], v[174:175], 0, v[172:173]
	s_mov_b64 s[28:29], 0
	ds_write_b16 v226, v137 offset:496

;     __device__ __forceinline__ bf16_t* H() const { return (bf16_t*)(ws + OFF_H); }
;     __device__ __forceinline__ bf16_t* VbT() const { return (bf16_t*)(ws + OFF_VbT); }
;     __device__ __forceinline__ bf16_t* VsbT() const { return (bf16_t*)(ws + OFF_VsbT); }
; DEV bf16_t f2bf(float f) { return (bf16_t)(pk_bf16(f, 0.f) & 0xffffu); }
; template <int H>
; DEV void epi1_group(const Params& p, int l, bool samp, int rbase, int g64, int fq, int fr, char* wsm, const f32x4 (&acc)[4][8]) {
;     ...
;         const int head = g64 - 38;
; #pragma unroll
;         for (int mi = 0; mi < 4; ++mi) {
;             const int row = rbase + mi * 16;
; #pragma unroll
;             for (int ni = 0; ni < 4; ++ni) {
;                 const f32x4 v = acc[mi][H * 4 + ni]; const int d = ni * 16 + cl, c = head * 64 + d;
;                 if (!samp) {
;                     *(f32x4*)(p.out + O_SV_P + ((size_t)l * SEQ + row) * 256 + c) = v;
; #pragma unroll
;                     for (int j = 0; j < 4; ++j) p.VbT()[(size_t)(head * 64 + d + j) * SEQ + row] = f2bf(v[j]);
;                 } else {
;                     const int s = row - SEQ, b = s >> 4, tt = s & 15;
;                     *(f32x4*)(p.out + O_SV_S + ((size_t)l * NSMP + s) * 256 + c) = v;
; #pragma unroll
;                     for (int j = 0; j < 4; ++j) p.VsbT()[((size_t)(b * 4 + head) * 64 + d + j) * KSP + PAST + tt] = f2bf(v[j]);
;                 }
.LBB0_1987:
	v_cvt_pk_bf16_f32 v137, v90, s0
	v_cvt_pk_bf16_f32 v133, v92, s0
	s_and_b64 vcc, exec, s[40:41]
	s_mov_b64 s[28:29], -1
	s_cbranch_vccnz .LBB0_1989
	v_mov_b32_e32 v131, v33
	v_lshl_add_u64 v[180:181], v[130:131], 2, v[176:177]
	flat_store_dwordx4 v[180:181], v[90:93] offset:64
	v_lshl_add_u64 v[180:181], v[168:169], 0, v[172:173]
	v_mov_b32_e32 v153, v33
	ds_write_b16 v226, v137 offset:2368
	v_lshlrev_b64 v[180:181], 15, v[152:153]
	v_lshl_add_u64 v[180:181], s[8:9], 0, v[180:181]
	v_cvt_pk_bf16_f32 v131, v91, s0
	v_lshl_add_u64 v[180:181], v[180:181], 0, v[172:173]
	v_mov_b32_e32 v141, v33
	ds_write_b16 v226, v131 offset:2512
	v_lshlrev_b64 v[180:181], 15, v[140:141]
	v_lshl_add_u64 v[180:181], s[8:9], 0, v[180:181]
	v_lshl_add_u64 v[180:181], v[180:181], 0, v[172:173]
	v_mov_b32_e32 v135, v33
	ds_write_b16 v226, v133 offset:2656
	v_lshlrev_b64 v[180:181], 15, v[134:135]
	v_lshl_add_u64 v[180:181], s[8:9], 0, v[180:181]
	v_cvt_pk_bf16_f32 v131, v93, s0
	v_lshl_add_u64 v[180:181], v[180:181], 0, v[172:173]
	s_mov_b64 s[28:29], 0
	ds_write_b16 v226, v131 offset:2800

;     __device__ __forceinline__ bf16_t* H() const { return (bf16_t*)(ws + OFF_H); }
;     __device__ __forceinline__ bf16_t* VbT() const { return (bf16_t*)(ws + OFF_VbT); }
;     __device__ __forceinline__ bf16_t* VsbT() const { return (bf16_t*)(ws + OFF_VsbT); }
; DEV bf16_t f2bf(float f) { return (bf16_t)(pk_bf16(f, 0.f) & 0xffffu); }
; template <int H>
; DEV void epi1_group(const Params& p, int l, bool samp, int rbase, int g64, int fq, int fr, char* wsm, const f32x4 (&acc)[4][8]) {
;     ...
;         const int head = g64 - 38;
; #pragma unroll
;         for (int mi = 0; mi < 4; ++mi) {
;             const int row = rbase + mi * 16;
; #pragma unroll
;             for (int ni = 0; ni < 4; ++ni) {
;                 const f32x4 v = acc[mi][H * 4 + ni]; const int d = ni * 16 + cl, c = head * 64 + d;
;                 if (!samp) {
;                     *(f32x4*)(p.out + O_SV_P + ((size_t)l * SEQ + row) * 256 + c) = v;
; #pragma unroll
;                     for (int j = 0; j < 4; ++j) p.VbT()[(size_t)(head * 64 + d + j) * SEQ + row] = f2bf(v[j]);
;                 } else {
;                     const int s = row - SEQ, b = s >> 4, tt = s & 15;
;                     *(f32x4*)(p.out + O_SV_S + ((size_t)l * NSMP + s) * 256 + c) = v;
; #pragma unroll
;                     for (int j = 0; j < 4; ++j) p.VsbT()[((size_t)(b * 4 + head) * 64 + d + j) * KSP + PAST + tt] = f2bf(v[j]);
;                 }
.LBB0_1991:
	v_cvt_pk_bf16_f32 v135, v86, s0
	v_cvt_pk_bf16_f32 v133, v88, s0
	s_and_b64 vcc, exec, s[40:41]
	s_mov_b64 s[28:29], -1
	s_cbranch_vccnz .LBB0_1993
	v_mov_b32_e32 v131, v33
	v_lshl_add_u64 v[180:181], v[130:131], 2, v[176:177]
	flat_store_dwordx4 v[180:181], v[86:89] offset:128
	v_lshl_add_u64 v[180:181], v[166:167], 0, v[172:173]
	v_mov_b32_e32 v161, v33
	ds_write_b16 v226, v135 offset:4672
	v_lshlrev_b64 v[180:181], 15, v[160:161]
	v_lshl_add_u64 v[180:181], s[8:9], 0, v[180:181]
	v_cvt_pk_bf16_f32 v131, v87, s0
	v_lshl_add_u64 v[180:181], v[180:181], 0, v[172:173]
	v_mov_b32_e32 v151, v33
	ds_write_b16 v226, v131 offset:4816
	v_lshlrev_b64 v[180:181], 15, v[150:151]
	v_lshl_add_u64 v[180:181], s[8:9], 0, v[180:181]
	v_lshl_add_u64 v[180:181], v[180:181], 0, v[172:173]
	v_mov_b32_e32 v139, v33
	ds_write_b16 v226, v133 offset:4960
	v_lshlrev_b64 v[180:181], 15, v[138:139]
	v_lshl_add_u64 v[180:181], s[8:9], 0, v[180:181]
	v_cvt_pk_bf16_f32 v131, v89, s0
	v_lshl_add_u64 v[180:181], v[180:181], 0, v[172:173]
	s_mov_b64 s[28:29], 0
	ds_write_b16 v226, v131 offset:5104

;     __device__ __forceinline__ bf16_t* H() const { return (bf16_t*)(ws + OFF_H); }
;     __device__ __forceinline__ bf16_t* VbT() const { return (bf16_t*)(ws + OFF_VbT); }
;     __device__ __forceinline__ bf16_t* VsbT() const { return (bf16_t*)(ws + OFF_VsbT); }
; DEV bf16_t f2bf(float f) { return (bf16_t)(pk_bf16(f, 0.f) & 0xffffu); }
; template <int H>
; DEV void epi1_group(const Params& p, int l, bool samp, int rbase, int g64, int fq, int fr, char* wsm, const f32x4 (&acc)[4][8]) {
;     ...
;         const int head = g64 - 38;
; #pragma unroll
;         for (int mi = 0; mi < 4; ++mi) {
;             const int row = rbase + mi * 16;
; #pragma unroll
;             for (int ni = 0; ni < 4; ++ni) {
;                 const f32x4 v = acc[mi][H * 4 + ni]; const int d = ni * 16 + cl, c = head * 64 + d;
;                 if (!samp) {
;                     *(f32x4*)(p.out + O_SV_P + ((size_t)l * SEQ + row) * 256 + c) = v;
; #pragma unroll
;                     for (int j = 0; j < 4; ++j) p.VbT()[(size_t)(head * 64 + d + j) * SEQ + row] = f2bf(v[j]);
;                 } else {
;                     const int s = row - SEQ, b = s >> 4, tt = s & 15;
;                     *(f32x4*)(p.out + O_SV_S + ((size_t)l * NSMP + s) * 256 + c) = v;
; #pragma unroll
;                     for (int j = 0; j < 4; ++j) p.VsbT()[((size_t)(b * 4 + head) * 64 + d + j) * KSP + PAST + tt] = f2bf(v[j]);
;                 }
.LBB0_1995:
	v_cvt_pk_bf16_f32 v135, v82, s0
	v_cvt_pk_bf16_f32 v133, v84, s0
	s_and_b64 vcc, exec, s[40:41]
	s_mov_b64 s[28:29], -1
	s_cbranch_vccnz .LBB0_1997
	v_mov_b32_e32 v131, v33
	v_lshl_add_u64 v[176:177], v[130:131], 2, v[176:177]
	flat_store_dwordx4 v[176:177], v[82:85] offset:192
	v_lshl_add_u64 v[176:177], v[164:165], 0, v[172:173]
	v_mov_b32_e32 v163, v33
	ds_write_b16 v226, v135 offset:6976
	v_lshlrev_b64 v[176:177], 15, v[162:163]
	v_lshl_add_u64 v[176:177], s[8:9], 0, v[176:177]
	v_cvt_pk_bf16_f32 v131, v83, s0
	v_lshl_add_u64 v[176:177], v[176:177], 0, v[172:173]
	v_mov_b32_e32 v159, v33
	ds_write_b16 v226, v131 offset:7120
	v_lshlrev_b64 v[176:177], 15, v[158:159]
	v_lshl_add_u64 v[176:177], s[8:9], 0, v[176:177]
	v_lshl_add_u64 v[176:177], v[176:177], 0, v[172:173]
	v_mov_b32_e32 v145, v33
	ds_write_b16 v226, v133 offset:7264
	v_lshlrev_b64 v[176:177], 15, v[144:145]
	v_lshl_add_u64 v[176:177], s[8:9], 0, v[176:177]
	v_cvt_pk_bf16_f32 v131, v85, s0
	v_lshl_add_u64 v[172:173], v[176:177], 0, v[172:173]
	s_mov_b64 s[28:29], 0
	ds_write_b16 v226, v131 offset:7408

;     __device__ __forceinline__ bf16_t* H() const { return (bf16_t*)(ws + OFF_H); }
;     __device__ __forceinline__ bf16_t* VbT() const { return (bf16_t*)(ws + OFF_VbT); }
;     __device__ __forceinline__ bf16_t* VsbT() const { return (bf16_t*)(ws + OFF_VsbT); }
; DEV bf16_t f2bf(float f) { return (bf16_t)(pk_bf16(f, 0.f) & 0xffffu); }
; template <int H>
; DEV void epi1_group(const Params& p, int l, bool samp, int rbase, int g64, int fq, int fr, char* wsm, const f32x4 (&acc)[4][8]) {
;     ...
;         const int head = g64 - 38;
; #pragma unroll
;         for (int mi = 0; mi < 4; ++mi) {
;             const int row = rbase + mi * 16;
; #pragma unroll
;             for (int ni = 0; ni < 4; ++ni) {
;                 const f32x4 v = acc[mi][H * 4 + ni]; const int d = ni * 16 + cl, c = head * 64 + d;
;                 if (!samp) {
;                     *(f32x4*)(p.out + O_SV_P + ((size_t)l * SEQ + row) * 256 + c) = v;
; #pragma unroll
;                     for (int j = 0; j < 4; ++j) p.VbT()[(size_t)(head * 64 + d + j) * SEQ + row] = f2bf(v[j]);
;                 } else {
;                     const int s = row - SEQ, b = s >> 4, tt = s & 15;
;                     *(f32x4*)(p.out + O_SV_S + ((size_t)l * NSMP + s) * 256 + c) = v;
; #pragma unroll
;                     for (int j = 0; j < 4; ++j) p.VsbT()[((size_t)(b * 4 + head) * 64 + d + j) * KSP + PAST + tt] = f2bf(v[j]);
;                 }
.LBB0_1999:
	v_or_b32_e32 v172, 48, v148
	v_ashrrev_i32_e32 v173, 31, v172
	v_lshlrev_b64 v[174:175], 10, v[172:173]
	v_cvt_pk_bf16_f32 v135, v78, s0
	v_cvt_pk_bf16_f32 v131, v80, s0
	s_mov_b64 s[28:29], -1
	s_and_b64 vcc, exec, s[40:41]
	v_lshl_add_u64 v[174:175], s[46:47], 0, v[174:175]
	v_lshlrev_b64 v[172:173], 1, v[172:173]
	s_cbranch_vccnz .LBB0_2001
	v_mov_b32_e32 v143, v33
	v_lshlrev_b64 v[142:143], 15, v[142:143]
	v_lshl_add_u64 v[142:143], s[8:9], 0, v[142:143]
	v_lshl_add_u64 v[176:177], v[32:33], 2, v[174:175]
	v_lshl_add_u64 v[170:171], v[170:171], 0, v[172:173]
	v_cvt_pk_bf16_f32 v133, v79, s0
	v_lshl_add_u64 v[142:143], v[142:143], 0, v[172:173]
	v_mov_b32_e32 v137, v33
	flat_store_dwordx4 v[176:177], v[78:81]
	ds_write_b16 v226, v135 offset:96
	ds_write_b16 v226, v133 offset:240
	v_lshlrev_b64 v[136:137], 15, v[136:137]
	v_mov_b32_e32 v133, v33
	v_lshl_add_u64 v[136:137], s[8:9], 0, v[136:137]
	v_lshlrev_b64 v[132:133], 15, v[132:133]
	v_lshl_add_u64 v[136:137], v[136:137], 0, v[172:173]
	v_lshl_add_u64 v[132:133], s[8:9], 0, v[132:133]
	ds_write_b16 v226, v131 offset:384
	v_cvt_pk_bf16_f32 v136, v81, s0
	v_lshl_add_u64 v[132:133], v[132:133], 0, v[172:173]
	s_mov_b64 s[28:29], 0
	ds_write_b16 v226, v136 offset:528

;     __device__ __forceinline__ bf16_t* H() const { return (bf16_t*)(ws + OFF_H); }
;     __device__ __forceinline__ bf16_t* VbT() const { return (bf16_t*)(ws + OFF_VbT); }
;     __device__ __forceinline__ bf16_t* VsbT() const { return (bf16_t*)(ws + OFF_VsbT); }
; DEV bf16_t f2bf(float f) { return (bf16_t)(pk_bf16(f, 0.f) & 0xffffu); }
; template <int H>
; DEV void epi1_group(const Params& p, int l, bool samp, int rbase, int g64, int fq, int fr, char* wsm, const f32x4 (&acc)[4][8]) {
;     ...
;         const int head = g64 - 38;
; #pragma unroll
;         for (int mi = 0; mi < 4; ++mi) {
;             const int row = rbase + mi * 16;
; #pragma unroll
;             for (int ni = 0; ni < 4; ++ni) {
;                 const f32x4 v = acc[mi][H * 4 + ni]; const int d = ni * 16 + cl, c = head * 64 + d;
;                 if (!samp) {
;                     *(f32x4*)(p.out + O_SV_P + ((size_t)l * SEQ + row) * 256 + c) = v;
; #pragma unroll
;                     for (int j = 0; j < 4; ++j) p.VbT()[(size_t)(head * 64 + d + j) * SEQ + row] = f2bf(v[j]);
;                 } else {
;                     const int s = row - SEQ, b = s >> 4, tt = s & 15;
;                     *(f32x4*)(p.out + O_SV_S + ((size_t)l * NSMP + s) * 256 + c) = v;
; #pragma unroll
;                     for (int j = 0; j < 4; ++j) p.VsbT()[((size_t)(b * 4 + head) * 64 + d + j) * KSP + PAST + tt] = f2bf(v[j]);
;                 }
.LBB0_2003:
	v_cvt_pk_bf16_f32 v142, v74, s0
	v_cvt_pk_bf16_f32 v139, v76, s0
	s_and_b64 vcc, exec, s[40:41]
	s_mov_b64 s[28:29], -1
	s_cbranch_vccnz .LBB0_2005
	v_mov_b32_e32 v153, v33
	v_lshlrev_b64 v[152:153], 15, v[152:153]
	v_mov_b32_e32 v141, v33
	v_mov_b32_e32 v135, v33
	v_mov_b32_e32 v131, v33
	v_lshl_add_u64 v[152:153], s[8:9], 0, v[152:153]
	v_lshlrev_b64 v[140:141], 15, v[140:141]
	v_lshlrev_b64 v[134:135], 15, v[134:135]
	v_lshl_add_u64 v[170:171], v[130:131], 2, v[174:175]
	v_lshl_add_u64 v[168:169], v[168:169], 0, v[172:173]
	v_cvt_pk_bf16_f32 v32, v75, s0
	v_lshl_add_u64 v[152:153], v[152:153], 0, v[172:173]
	v_lshl_add_u64 v[140:141], s[8:9], 0, v[140:141]
	v_lshl_add_u64 v[134:135], s[8:9], 0, v[134:135]
	flat_store_dwordx4 v[170:171], v[74:77] offset:64
	ds_write_b16 v226, v142 offset:2400
	ds_write_b16 v226, v32 offset:2544
	v_lshl_add_u64 v[140:141], v[140:141], 0, v[172:173]
	v_cvt_pk_bf16_f32 v32, v77, s0
	v_lshl_add_u64 v[134:135], v[134:135], 0, v[172:173]
	s_mov_b64 s[28:29], 0
	ds_write_b16 v226, v139 offset:2688
	ds_write_b16 v226, v32 offset:2832

;     __device__ __forceinline__ bf16_t* H() const { return (bf16_t*)(ws + OFF_H); }
;     __device__ __forceinline__ bf16_t* VbT() const { return (bf16_t*)(ws + OFF_VbT); }
;     __device__ __forceinline__ bf16_t* VsbT() const { return (bf16_t*)(ws + OFF_VsbT); }
; DEV bf16_t f2bf(float f) { return (bf16_t)(pk_bf16(f, 0.f) & 0xffffu); }
; template <int H>
; DEV void epi1_group(const Params& p, int l, bool samp, int rbase, int g64, int fq, int fr, char* wsm, const f32x4 (&acc)[4][8]) {
;     ...
;         const int head = g64 - 38;
; #pragma unroll
;         for (int mi = 0; mi < 4; ++mi) {
;             const int row = rbase + mi * 16;
; #pragma unroll
;             for (int ni = 0; ni < 4; ++ni) {
;                 const f32x4 v = acc[mi][H * 4 + ni]; const int d = ni * 16 + cl, c = head * 64 + d;
;                 if (!samp) {
;                     *(f32x4*)(p.out + O_SV_P + ((size_t)l * SEQ + row) * 256 + c) = v;
; #pragma unroll
;                     for (int j = 0; j < 4; ++j) p.VbT()[(size_t)(head * 64 + d + j) * SEQ + row] = f2bf(v[j]);
;                 } else {
;                     const int s = row - SEQ, b = s >> 4, tt = s & 15;
;                     *(f32x4*)(p.out + O_SV_S + ((size_t)l * NSMP + s) * 256 + c) = v;
; #pragma unroll
;                     for (int j = 0; j < 4; ++j) p.VsbT()[((size_t)(b * 4 + head) * 64 + d + j) * KSP + PAST + tt] = f2bf(v[j]);
;                 }
.LBB0_2007:
	v_cvt_pk_bf16_f32 v135, v70, s0
	v_cvt_pk_bf16_f32 v134, v72, s0
	s_and_b64 vcc, exec, s[40:41]
	s_mov_b64 s[28:29], -1
	s_cbranch_vccnz .LBB0_2009
	v_mov_b32_e32 v131, v33
	v_lshl_add_u64 v[140:141], v[130:131], 2, v[174:175]
	flat_store_dwordx4 v[140:141], v[70:73] offset:128
	v_lshl_add_u64 v[140:141], v[166:167], 0, v[172:173]
	v_mov_b32_e32 v161, v33
	ds_write_b16 v226, v135 offset:4704
	v_lshlrev_b64 v[140:141], 15, v[160:161]
	v_lshl_add_u64 v[140:141], s[8:9], 0, v[140:141]
	v_cvt_pk_bf16_f32 v32, v71, s0
	v_lshl_add_u64 v[140:141], v[140:141], 0, v[172:173]
	v_mov_b32_e32 v151, v33
	v_mov_b32_e32 v139, v33
	ds_write_b16 v226, v32 offset:4848
	v_lshlrev_b64 v[140:141], 15, v[150:151]
	v_lshlrev_b64 v[138:139], 15, v[138:139]
	v_lshl_add_u64 v[140:141], s[8:9], 0, v[140:141]
	v_lshl_add_u64 v[138:139], s[8:9], 0, v[138:139]
	v_lshl_add_u64 v[140:141], v[140:141], 0, v[172:173]
	v_cvt_pk_bf16_f32 v32, v73, s0
	v_lshl_add_u64 v[138:139], v[138:139], 0, v[172:173]
	s_mov_b64 s[28:29], 0
	ds_write_b16 v226, v134 offset:4992
	ds_write_b16 v226, v32 offset:5136

;     __device__ __forceinline__ bf16_t* H() const { return (bf16_t*)(ws + OFF_H); }
;     __device__ __forceinline__ bf16_t* VbT() const { return (bf16_t*)(ws + OFF_VbT); }
;     __device__ __forceinline__ bf16_t* VsbT() const { return (bf16_t*)(ws + OFF_VsbT); }
; DEV bf16_t f2bf(float f) { return (bf16_t)(pk_bf16(f, 0.f) & 0xffffu); }
; template <int H>
; DEV void epi1_group(const Params& p, int l, bool samp, int rbase, int g64, int fq, int fr, char* wsm, const f32x4 (&acc)[4][8]) {
;     ...
;         const int head = g64 - 38;
; #pragma unroll
;         for (int mi = 0; mi < 4; ++mi) {
;             const int row = rbase + mi * 16;
; #pragma unroll
;             for (int ni = 0; ni < 4; ++ni) {
;                 const f32x4 v = acc[mi][H * 4 + ni]; const int d = ni * 16 + cl, c = head * 64 + d;
;                 if (!samp) {
;                     *(f32x4*)(p.out + O_SV_P + ((size_t)l * SEQ + row) * 256 + c) = v;
; #pragma unroll
;                     for (int j = 0; j < 4; ++j) p.VbT()[(size_t)(head * 64 + d + j) * SEQ + row] = f2bf(v[j]);
;                 } else {
;                     const int s = row - SEQ, b = s >> 4, tt = s & 15;
;                     *(f32x4*)(p.out + O_SV_S + ((size_t)l * NSMP + s) * 256 + c) = v;
; #pragma unroll
;                     for (int j = 0; j < 4; ++j) p.VsbT()[((size_t)(b * 4 + head) * 64 + d + j) * KSP + PAST + tt] = f2bf(v[j]);
;                 }
.LBB0_2011:
	v_cvt_pk_bf16_f32 v135, v66, s0
	v_cvt_pk_bf16_f32 v134, v68, s0
	s_and_b64 vcc, exec, s[40:41]
	s_mov_b64 s[28:29], -1
	s_cbranch_vccnz .LBB0_2013
	v_mov_b32_e32 v131, v33
	v_lshl_add_u64 v[138:139], v[130:131], 2, v[174:175]
	flat_store_dwordx4 v[138:139], v[66:69] offset:192
	v_lshl_add_u64 v[138:139], v[164:165], 0, v[172:173]
	v_mov_b32_e32 v163, v33
	ds_write_b16 v226, v135 offset:7008
	v_lshlrev_b64 v[138:139], 15, v[162:163]
	v_lshl_add_u64 v[138:139], s[8:9], 0, v[138:139]
	v_cvt_pk_bf16_f32 v32, v67, s0
	v_lshl_add_u64 v[138:139], v[138:139], 0, v[172:173]
	v_mov_b32_e32 v159, v33
	ds_write_b16 v226, v32 offset:7152
	v_lshlrev_b64 v[138:139], 15, v[158:159]
	v_lshl_add_u64 v[138:139], s[8:9], 0, v[138:139]
	v_lshl_add_u64 v[138:139], v[138:139], 0, v[172:173]
	v_mov_b32_e32 v145, v33
	ds_write_b16 v226, v134 offset:7296
	v_lshlrev_b64 v[138:139], 15, v[144:145]
	v_lshl_add_u64 v[138:139], s[8:9], 0, v[138:139]
	v_cvt_pk_bf16_f32 v32, v69, s0
	v_lshl_add_u64 v[138:139], v[138:139], 0, v[172:173]
	s_mov_b64 s[28:29], 0
	ds_write_b16 v226, v32 offset:7440

;     __device__ __forceinline__ bf16_t* VbT() const { return (bf16_t*)(ws + OFF_VbT); }
; DEV bf16_t f2bf(float f) { return (bf16_t)(pk_bf16(f, 0.f) & 0xffffu); }
; template <int H>
; DEV void epi1_group(const Params& p, int l, bool samp, int rbase, int g64, int fq, int fr, char* wsm, const f32x4 (&acc)[4][8]) {
;     ...
;                     for (int j = 0; j < 4; ++j) p.VbT()[(size_t)(head * 64 + d + j) * SEQ + row] = f2bf(v[j]);
.LBB0_2015:
	s_andn2_b64 vcc, exec, s[42:43]
	s_cbranch_vccnz .Lvt_skip_0
	v_and_b32_e32 v234, 63, v186
	v_lshrrev_b32_e32 v235, 3, v234
	v_mul_u32_u24_e32 v235, 0x90, v235
	v_and_b32_e32 v234, 7, v234
	v_lshl_add_u32 v234, v234, 4, v235
	v_lshrrev_b32_e32 v235, 6, v186
	v_mul_u32_u24_e32 v235, 0x4400, v235
	v_add_u32_e32 v234, v234, v235
	s_waitcnt lgkmcnt(0)
	ds_read_b128 v[236:239], v234 offset:0
	s_waitcnt lgkmcnt(0)
	flat_store_dwordx4 v[228:229], v[236:239]
	v_lshl_add_u64 v[228:229], v[228:229], 0, v[232:233]
	ds_read_b128 v[240:243], v234 offset:1152
	s_waitcnt lgkmcnt(0)
	flat_store_dwordx4 v[228:229], v[240:243]
	v_lshl_add_u64 v[228:229], v[228:229], 0, v[232:233]
	ds_read_b128 v[236:239], v234 offset:2304
	s_waitcnt lgkmcnt(0)
	flat_store_dwordx4 v[228:229], v[236:239]
	v_lshl_add_u64 v[228:229], v[228:229], 0, v[232:233]
	ds_read_b128 v[240:243], v234 offset:3456
	s_waitcnt lgkmcnt(0)
	flat_store_dwordx4 v[228:229], v[240:243]
	v_lshl_add_u64 v[228:229], v[228:229], 0, v[232:233]
	ds_read_b128 v[236:239], v234 offset:4608
	s_waitcnt lgkmcnt(0)
	flat_store_dwordx4 v[228:229], v[236:239]
	v_lshl_add_u64 v[228:229], v[228:229], 0, v[232:233]
	ds_read_b128 v[240:243], v234 offset:5760
	s_waitcnt lgkmcnt(0)
	flat_store_dwordx4 v[228:229], v[240:243]
	v_lshl_add_u64 v[228:229], v[228:229], 0, v[232:233]
	ds_read_b128 v[236:239], v234 offset:6912
	s_waitcnt lgkmcnt(0)
	flat_store_dwordx4 v[228:229], v[236:239]
	v_lshl_add_u64 v[228:229], v[228:229], 0, v[232:233]
	ds_read_b128 v[240:243], v234 offset:8064
	s_waitcnt lgkmcnt(0)
	flat_store_dwordx4 v[228:229], v[240:243]
	v_lshl_add_u64 v[228:229], v[228:229], 0, v[232:233]

;     __device__ __forceinline__ bf16_t* H() const { return (bf16_t*)(ws + OFF_H); }
;     __device__ __forceinline__ bf16_t* VfT() const { return (bf16_t*)(ws + OFF_VfT); }
; DEV bf16_t f2bf(float f) { return (bf16_t)(pk_bf16(f, 0.f) & 0xffffu); }
; template <int H>
; DEV void epi1_group(const Params& p, int l, bool samp, int rbase, int g64, int fq, int fr, char* wsm, const f32x4 (&acc)[4][8]) {
;     ...
;         const int head = g64 - 24;
; #pragma unroll
;         for (int mi = 0; mi < 4; ++mi) {
;             const int row = rbase + mi * 16;
; #pragma unroll
;             for (int ni = 0; ni < 4; ++ni) {
;                 const f32x4 v = acc[mi][H * 4 + ni]; const int d = ni * 16 + cl, c = head * 64 + d;
;                 if (!samp) {
;                     *(f32x4*)(p.out + O_FV_P + ((size_t)l * SEQ + row) * 384 + c) = v;
; #pragma unroll
;                     for (int j = 0; j < 4; ++j) p.VfT()[(size_t)(head * 64 + d + j) * SEQ + row] = f2bf(v[j]);
.LBB0_2085:
	s_andn2_saveexec_b64 s[0:1], s[66:67]
	s_cbranch_execz .LBB0_2150
	v_ashrrev_i32_e32 v149, 31, v148
	v_subrev_u32_e32 v132, 24, v206
	v_lshl_add_u64 v[130:131], s[12:13], 0, v[148:149]
	s_movk_i32 s28, 0x600
	v_lshlrev_b32_e32 v133, 6, v132
	v_mad_u64_u32 v[134:135], s[22:23], v130, s28, 0
	v_mad_i32_i24 v135, v131, s28, v135
	v_or_b32_e32 v32, v133, v147
	v_cndmask_b32_e64 v136, 0, 1, s[42:43]
	v_cvt_pk_bf16_f32 v131, v126, s0
	v_cvt_pk_bf16_f32 v130, v128, s0
	s_mov_b64 s[22:23], -1
	v_cmp_ne_u32_e64 s[40:41], 1, v136
	s_andn2_b64 vcc, exec, s[42:43]
	v_lshl_add_u64 v[172:173], s[56:57], 0, v[134:135]
	v_lshlrev_b64 v[166:167], 15, v[32:33]
	v_lshl_add_u64 v[170:171], v[148:149], 1, s[16:17]
	v_or_b32_e32 v144, 1, v32
	v_or_b32_e32 v138, 2, v32
	v_or_b32_e32 v134, 3, v32
	s_cbranch_vccnz .LBB0_2088
	v_lshl_add_u64 v[136:137], v[32:33], 2, v[172:173]
	flat_store_dwordx4 v[136:137], v[126:129]
	v_lshl_add_u64 v[136:137], v[170:171], 0, v[166:167]
	v_mov_b32_e32 v145, v33
	v_lshrrev_b32_e32 v226, 6, v186
	v_mul_u32_u24_e32 v226, 0x4400, v226
	v_bfe_u32 v227, v186, 4, 2
	v_mul_u32_u24_e32 v230, 0x240, v227
	v_add_u32_e32 v226, v226, v230
	v_and_b32_e32 v230, 15, v186
	v_lshl_add_u32 v226, v230, 1, v226
	v_mov_b32_e32 v228, v136
	v_mov_b32_e32 v229, v137
	v_and_b32_e32 v231, 7, v230
	v_lshlrev_b32_e32 v231, 4, v231
	v_lshlrev_b32_e32 v234, 1, v230
	v_sub_u32_e32 v231, v231, v234
	v_lshrrev_b32_e32 v234, 3, v230
	v_lshl_add_u32 v231, v234, 15, v231
	v_lshlrev_b32_e32 v234, 16, v227
	v_sub_u32_e32 v234, v231, v234
	v_ashrrev_i32_e32 v235, 31, v234
	v_lshl_add_u64 v[228:229], v[228:229], 0, v[234:235]
	v_mov_b32_e32 v232, 0x40000
	v_mov_b32_e32 v233, 0
	ds_write_b16 v226, v131 offset:0
	v_lshlrev_b64 v[136:137], 15, v[144:145]
	v_cvt_pk_bf16_f32 v135, v127, s0
	v_lshl_add_u64 v[136:137], v[170:171], 0, v[136:137]
	v_mov_b32_e32 v139, v33
	ds_write_b16 v226, v135 offset:144
	v_lshlrev_b64 v[136:137], 15, v[138:139]
	v_lshl_add_u64 v[136:137], v[170:171], 0, v[136:137]
	v_mov_b32_e32 v135, v33
	ds_write_b16 v226, v130 offset:288
	v_lshlrev_b64 v[136:137], 15, v[134:135]
	v_cvt_pk_bf16_f32 v139, v129, s0
	v_lshl_add_u64 v[136:137], v[170:171], 0, v[136:137]
	s_mov_b64 s[22:23], 0
	ds_write_b16 v226, v139 offset:432

;     __device__ __forceinline__ bf16_t* H() const { return (bf16_t*)(ws + OFF_H); }
;     __device__ __forceinline__ bf16_t* VfT() const { return (bf16_t*)(ws + OFF_VfT); }
; DEV bf16_t f2bf(float f) { return (bf16_t)(pk_bf16(f, 0.f) & 0xffffu); }
; template <int H>
; DEV void epi1_group(const Params& p, int l, bool samp, int rbase, int g64, int fq, int fr, char* wsm, const f32x4 (&acc)[4][8]) {
;     ...
;         const int head = g64 - 24;
; #pragma unroll
;         for (int mi = 0; mi < 4; ++mi) {
;             const int row = rbase + mi * 16;
; #pragma unroll
;             for (int ni = 0; ni < 4; ++ni) {
;                 const f32x4 v = acc[mi][H * 4 + ni]; const int d = ni * 16 + cl, c = head * 64 + d;
;                 if (!samp) {
;                     *(f32x4*)(p.out + O_FV_P + ((size_t)l * SEQ + row) * 384 + c) = v;
; #pragma unroll
;                     for (int j = 0; j < 4; ++j) p.VfT()[(size_t)(head * 64 + d + j) * SEQ + row] = f2bf(v[j]);
.LBB0_2090:
	v_or_b32_e32 v149, 16, v147
	v_or_b32_e32 v136, v133, v149
	v_mov_b32_e32 v137, v33
	v_cvt_pk_bf16_f32 v139, v122, s0
	v_cvt_pk_bf16_f32 v135, v124, s0
	s_mov_b64 s[22:23], -1
	s_and_b64 vcc, exec, s[40:41]
	v_add_u32_e32 v130, v133, v147
	v_lshlrev_b64 v[168:169], 15, v[136:137]
	v_or_b32_e32 v158, 1, v136
	v_or_b32_e32 v142, 2, v136
	v_or_b32_e32 v136, 3, v136
	s_cbranch_vccnz .LBB0_2092
	v_mov_b32_e32 v131, v33
	v_lshl_add_u64 v[140:141], v[130:131], 2, v[172:173]
	flat_store_dwordx4 v[140:141], v[122:125] offset:64
	v_lshl_add_u64 v[140:141], v[170:171], 0, v[168:169]
	v_mov_b32_e32 v159, v33
	ds_write_b16 v226, v139 offset:2304
	v_lshlrev_b64 v[140:141], 15, v[158:159]
	v_cvt_pk_bf16_f32 v131, v123, s0
	v_lshl_add_u64 v[140:141], v[170:171], 0, v[140:141]
	v_mov_b32_e32 v143, v33
	ds_write_b16 v226, v131 offset:2448
	v_lshlrev_b64 v[140:141], 15, v[142:143]
	v_lshl_add_u64 v[140:141], v[170:171], 0, v[140:141]
	v_mov_b32_e32 v137, v33
	ds_write_b16 v226, v135 offset:2592
	v_lshlrev_b64 v[140:141], 15, v[136:137]
	v_cvt_pk_bf16_f32 v131, v125, s0
	v_lshl_add_u64 v[140:141], v[170:171], 0, v[140:141]
	s_mov_b64 s[22:23], 0
	ds_write_b16 v226, v131 offset:2736

;     __device__ __forceinline__ bf16_t* H() const { return (bf16_t*)(ws + OFF_H); }
;     __device__ __forceinline__ bf16_t* VfT() const { return (bf16_t*)(ws + OFF_VfT); }
; DEV bf16_t f2bf(float f) { return (bf16_t)(pk_bf16(f, 0.f) & 0xffffu); }
; template <int H>
; DEV void epi1_group(const Params& p, int l, bool samp, int rbase, int g64, int fq, int fr, char* wsm, const f32x4 (&acc)[4][8]) {
;     ...
;         const int head = g64 - 24;
; #pragma unroll
;         for (int mi = 0; mi < 4; ++mi) {
;             const int row = rbase + mi * 16;
; #pragma unroll
;             for (int ni = 0; ni < 4; ++ni) {
;                 const f32x4 v = acc[mi][H * 4 + ni]; const int d = ni * 16 + cl, c = head * 64 + d;
;                 if (!samp) {
;                     *(f32x4*)(p.out + O_FV_P + ((size_t)l * SEQ + row) * 384 + c) = v;
; #pragma unroll
;                     for (int j = 0; j < 4; ++j) p.VfT()[(size_t)(head * 64 + d + j) * SEQ + row] = f2bf(v[j]);
.LBB0_2094:
	v_or_b32_e32 v207, 32, v147
	v_or_b32_e32 v140, v133, v207
	v_mov_b32_e32 v141, v33
	v_cvt_pk_bf16_f32 v137, v118, s0
	v_cvt_pk_bf16_f32 v135, v120, s0
	s_mov_b64 s[22:23], -1
	s_and_b64 vcc, exec, s[40:41]
	v_lshlrev_b64 v[174:175], 15, v[140:141]
	v_or_b32_e32 v162, 1, v140
	v_or_b32_e32 v152, 2, v140
	v_or_b32_e32 v140, 3, v140
	s_cbranch_vccnz .LBB0_2096
	v_mov_b32_e32 v131, v33
	v_lshl_add_u64 v[150:151], v[130:131], 2, v[172:173]
	flat_store_dwordx4 v[150:151], v[118:121] offset:128
	v_lshl_add_u64 v[150:151], v[170:171], 0, v[174:175]
	v_mov_b32_e32 v163, v33
	ds_write_b16 v226, v137 offset:4608
	v_lshlrev_b64 v[150:151], 15, v[162:163]
	v_cvt_pk_bf16_f32 v131, v119, s0
	v_lshl_add_u64 v[150:151], v[170:171], 0, v[150:151]
	v_mov_b32_e32 v153, v33
	ds_write_b16 v226, v131 offset:4752
	v_lshlrev_b64 v[150:151], 15, v[152:153]
	v_lshl_add_u64 v[150:151], v[170:171], 0, v[150:151]
	v_mov_b32_e32 v141, v33
	ds_write_b16 v226, v135 offset:4896
	v_lshlrev_b64 v[150:151], 15, v[140:141]
	v_cvt_pk_bf16_f32 v131, v121, s0
	v_lshl_add_u64 v[150:151], v[170:171], 0, v[150:151]
	s_mov_b64 s[22:23], 0
	ds_write_b16 v226, v131 offset:5040

.LBB0_2098:
	v_or_b32_e32 v208, 48, v147
	v_or_b32_e32 v150, v133, v208
	v_mov_b32_e32 v151, v33
	v_cvt_pk_bf16_f32 v135, v114, s0
	v_cvt_pk_bf16_f32 v133, v116, s0
	s_mov_b64 s[22:23], -1
	s_and_b64 vcc, exec, s[40:41]
	v_lshlrev_b64 v[176:177], 15, v[150:151]
	v_or_b32_e32 v164, 1, v150
	v_or_b32_e32 v160, 2, v150
	v_or_b32_e32 v150, 3, v150
	s_cbranch_vccnz .LBB0_2100
	v_mov_b32_e32 v131, v33
	v_lshl_add_u64 v[172:173], v[130:131], 2, v[172:173]
	flat_store_dwordx4 v[172:173], v[114:117] offset:192
	v_lshl_add_u64 v[172:173], v[170:171], 0, v[176:177]
	v_mov_b32_e32 v165, v33
	ds_write_b16 v226, v135 offset:6912
	v_lshlrev_b64 v[172:173], 15, v[164:165]
	v_cvt_pk_bf16_f32 v131, v115, s0
	v_lshl_add_u64 v[172:173], v[170:171], 0, v[172:173]
	v_mov_b32_e32 v161, v33
	ds_write_b16 v226, v131 offset:7056
	v_lshlrev_b64 v[172:173], 15, v[160:161]
	v_lshl_add_u64 v[172:173], v[170:171], 0, v[172:173]
	v_mov_b32_e32 v151, v33
	ds_write_b16 v226, v133 offset:7200
	v_lshlrev_b64 v[172:173], 15, v[150:151]
	v_cvt_pk_bf16_f32 v131, v117, s0
	v_lshl_add_u64 v[170:171], v[170:171], 0, v[172:173]
	s_mov_b64 s[22:23], 0
	ds_write_b16 v226, v131 offset:7344

.LBB0_2102:
	v_or_b32_e32 v170, 16, v148
	v_ashrrev_i32_e32 v171, 31, v170
	v_lshl_add_u64 v[172:173], s[12:13], 0, v[170:171]
	s_movk_i32 s28, 0x600
	v_mad_u64_u32 v[178:179], s[22:23], v172, s28, 0
	v_mad_i32_i24 v179, v173, s28, v179
	v_cvt_pk_bf16_f32 v133, v110, s0
	v_cvt_pk_bf16_f32 v131, v112, s0
	s_mov_b64 s[22:23], -1
	s_and_b64 vcc, exec, s[40:41]
	v_lshl_add_u64 v[180:181], s[56:57], 0, v[178:179]
	v_lshlrev_b64 v[178:179], 1, v[170:171]
	v_lshl_add_u64 v[172:173], s[16:17], 0, v[166:167]
	s_cbranch_vccnz .LBB0_2104
	v_lshl_add_u64 v[166:167], v[32:33], 2, v[180:181]
	flat_store_dwordx4 v[166:167], v[110:113]
	v_lshl_add_u64 v[166:167], v[172:173], 0, v[178:179]
	v_mov_b32_e32 v145, v33
	ds_write_b16 v226, v133 offset:32
	v_lshlrev_b64 v[166:167], 15, v[144:145]
	v_lshl_add_u64 v[166:167], s[16:17], 0, v[166:167]
	v_cvt_pk_bf16_f32 v135, v111, s0
	v_lshl_add_u64 v[166:167], v[166:167], 0, v[178:179]
	v_mov_b32_e32 v139, v33
	ds_write_b16 v226, v135 offset:176
	v_lshlrev_b64 v[166:167], 15, v[138:139]
	v_lshl_add_u64 v[166:167], s[16:17], 0, v[166:167]
	v_lshl_add_u64 v[166:167], v[166:167], 0, v[178:179]
	v_mov_b32_e32 v135, v33
	ds_write_b16 v226, v131 offset:320
	v_lshlrev_b64 v[166:167], 15, v[134:135]
	v_lshl_add_u64 v[166:167], s[16:17], 0, v[166:167]
	v_cvt_pk_bf16_f32 v137, v113, s0
	v_lshl_add_u64 v[166:167], v[166:167], 0, v[178:179]
	s_mov_b64 s[22:23], 0
	ds_write_b16 v226, v137 offset:464

.LBB0_2106:
	v_cvt_pk_bf16_f32 v135, v106, s0
	v_cvt_pk_bf16_f32 v133, v108, s0
	s_mov_b64 s[22:23], -1
	s_and_b64 vcc, exec, s[40:41]
	v_lshl_add_u64 v[170:171], s[16:17], 0, v[168:169]
	s_cbranch_vccnz .LBB0_2108
	v_mov_b32_e32 v131, v33
	v_lshl_add_u64 v[166:167], v[130:131], 2, v[180:181]
	flat_store_dwordx4 v[166:167], v[106:109] offset:64
	v_lshl_add_u64 v[166:167], v[170:171], 0, v[178:179]
	v_mov_b32_e32 v159, v33
	ds_write_b16 v226, v135 offset:2336
	v_lshlrev_b64 v[166:167], 15, v[158:159]
	v_lshl_add_u64 v[166:167], s[16:17], 0, v[166:167]
	v_cvt_pk_bf16_f32 v131, v107, s0
	v_lshl_add_u64 v[166:167], v[166:167], 0, v[178:179]
	v_mov_b32_e32 v143, v33
	ds_write_b16 v226, v131 offset:2480
	v_lshlrev_b64 v[166:167], 15, v[142:143]
	v_lshl_add_u64 v[166:167], s[16:17], 0, v[166:167]
	v_lshl_add_u64 v[166:167], v[166:167], 0, v[178:179]
	v_mov_b32_e32 v137, v33
	ds_write_b16 v226, v133 offset:2624
	v_lshlrev_b64 v[166:167], 15, v[136:137]
	v_lshl_add_u64 v[166:167], s[16:17], 0, v[166:167]
	v_cvt_pk_bf16_f32 v131, v109, s0
	v_lshl_add_u64 v[166:167], v[166:167], 0, v[178:179]
	s_mov_b64 s[22:23], 0
	ds_write_b16 v226, v131 offset:2768

.LBB0_2110:
	v_cvt_pk_bf16_f32 v135, v102, s0
	v_cvt_pk_bf16_f32 v133, v104, s0
	s_mov_b64 s[22:23], -1
	s_and_b64 vcc, exec, s[40:41]
	v_lshl_add_u64 v[168:169], s[16:17], 0, v[174:175]
	s_cbranch_vccnz .LBB0_2112
	v_mov_b32_e32 v131, v33
	v_lshl_add_u64 v[166:167], v[130:131], 2, v[180:181]
	flat_store_dwordx4 v[166:167], v[102:105] offset:128
	v_lshl_add_u64 v[166:167], v[168:169], 0, v[178:179]
	v_mov_b32_e32 v163, v33
	ds_write_b16 v226, v135 offset:4640
	v_lshlrev_b64 v[166:167], 15, v[162:163]
	v_lshl_add_u64 v[166:167], s[16:17], 0, v[166:167]
	v_cvt_pk_bf16_f32 v131, v103, s0
	v_lshl_add_u64 v[166:167], v[166:167], 0, v[178:179]
	v_mov_b32_e32 v153, v33
	ds_write_b16 v226, v131 offset:4784
	v_lshlrev_b64 v[166:167], 15, v[152:153]
	v_lshl_add_u64 v[166:167], s[16:17], 0, v[166:167]
	v_lshl_add_u64 v[166:167], v[166:167], 0, v[178:179]
	v_mov_b32_e32 v141, v33
	ds_write_b16 v226, v133 offset:4928
	v_lshlrev_b64 v[166:167], 15, v[140:141]
	v_lshl_add_u64 v[166:167], s[16:17], 0, v[166:167]
	v_cvt_pk_bf16_f32 v131, v105, s0
	v_lshl_add_u64 v[166:167], v[166:167], 0, v[178:179]
	s_mov_b64 s[22:23], 0
	ds_write_b16 v226, v131 offset:5072

.LBB0_2114:
	v_cvt_pk_bf16_f32 v135, v98, s0
	v_cvt_pk_bf16_f32 v133, v100, s0
	s_mov_b64 s[22:23], -1
	s_and_b64 vcc, exec, s[40:41]
	v_lshl_add_u64 v[166:167], s[16:17], 0, v[176:177]
	s_cbranch_vccnz .LBB0_2116
	v_mov_b32_e32 v131, v33
	v_lshl_add_u64 v[174:175], v[130:131], 2, v[180:181]
	flat_store_dwordx4 v[174:175], v[98:101] offset:192
	v_lshl_add_u64 v[174:175], v[166:167], 0, v[178:179]
	v_mov_b32_e32 v165, v33
	ds_write_b16 v226, v135 offset:6944
	v_lshlrev_b64 v[174:175], 15, v[164:165]
	v_lshl_add_u64 v[174:175], s[16:17], 0, v[174:175]
	v_cvt_pk_bf16_f32 v131, v99, s0
	v_lshl_add_u64 v[174:175], v[174:175], 0, v[178:179]
	v_mov_b32_e32 v161, v33
	ds_write_b16 v226, v131 offset:7088
	v_lshlrev_b64 v[174:175], 15, v[160:161]
	v_lshl_add_u64 v[174:175], s[16:17], 0, v[174:175]
	v_lshl_add_u64 v[174:175], v[174:175], 0, v[178:179]
	v_mov_b32_e32 v151, v33
	ds_write_b16 v226, v133 offset:7232
	v_lshlrev_b64 v[174:175], 15, v[150:151]
	v_lshl_add_u64 v[174:175], s[16:17], 0, v[174:175]
	v_cvt_pk_bf16_f32 v131, v101, s0
	v_lshl_add_u64 v[174:175], v[174:175], 0, v[178:179]
	s_mov_b64 s[22:23], 0
	ds_write_b16 v226, v131 offset:7376

.LBB0_2118:
	v_or_b32_e32 v174, 32, v148
	v_ashrrev_i32_e32 v175, 31, v174
	v_lshl_add_u64 v[176:177], s[12:13], 0, v[174:175]
	s_movk_i32 s28, 0x600
	v_mad_u64_u32 v[178:179], s[22:23], v176, s28, 0
	v_mad_i32_i24 v179, v177, s28, v179
	v_cvt_pk_bf16_f32 v133, v94, s0
	v_cvt_pk_bf16_f32 v131, v96, s0
	s_mov_b64 s[22:23], -1
	s_and_b64 vcc, exec, s[40:41]
	v_lshl_add_u64 v[176:177], s[56:57], 0, v[178:179]
	v_lshlrev_b64 v[174:175], 1, v[174:175]
	s_cbranch_vccnz .LBB0_2120
	v_lshl_add_u64 v[178:179], v[32:33], 2, v[176:177]
	flat_store_dwordx4 v[178:179], v[94:97]
	v_lshl_add_u64 v[178:179], v[172:173], 0, v[174:175]
	v_mov_b32_e32 v145, v33
	ds_write_b16 v226, v133 offset:64
	v_lshlrev_b64 v[178:179], 15, v[144:145]
	v_lshl_add_u64 v[178:179], s[16:17], 0, v[178:179]
	v_cvt_pk_bf16_f32 v135, v95, s0
	v_lshl_add_u64 v[178:179], v[178:179], 0, v[174:175]
	v_mov_b32_e32 v139, v33
	ds_write_b16 v226, v135 offset:208
	v_lshlrev_b64 v[178:179], 15, v[138:139]
	v_lshl_add_u64 v[178:179], s[16:17], 0, v[178:179]
	v_lshl_add_u64 v[178:179], v[178:179], 0, v[174:175]
	v_mov_b32_e32 v135, v33
	ds_write_b16 v226, v131 offset:352
	v_lshlrev_b64 v[178:179], 15, v[134:135]
	v_lshl_add_u64 v[178:179], s[16:17], 0, v[178:179]
	v_cvt_pk_bf16_f32 v137, v97, s0
	v_lshl_add_u64 v[178:179], v[178:179], 0, v[174:175]
	s_mov_b64 s[22:23], 0
	ds_write_b16 v226, v137 offset:496

.LBB0_2122:
	v_cvt_pk_bf16_f32 v135, v90, s0
	v_cvt_pk_bf16_f32 v133, v92, s0
	s_and_b64 vcc, exec, s[40:41]
	s_mov_b64 s[22:23], -1
	s_cbranch_vccnz .LBB0_2124
	v_mov_b32_e32 v131, v33
	v_lshl_add_u64 v[182:183], v[130:131], 2, v[176:177]
	flat_store_dwordx4 v[182:183], v[90:93] offset:64
	v_lshl_add_u64 v[182:183], v[170:171], 0, v[174:175]
	v_mov_b32_e32 v159, v33
	ds_write_b16 v226, v135 offset:2368
	v_lshlrev_b64 v[182:183], 15, v[158:159]
	v_lshl_add_u64 v[182:183], s[16:17], 0, v[182:183]
	v_cvt_pk_bf16_f32 v131, v91, s0
	v_lshl_add_u64 v[182:183], v[182:183], 0, v[174:175]
	v_mov_b32_e32 v143, v33
	ds_write_b16 v226, v131 offset:2512
	v_lshlrev_b64 v[182:183], 15, v[142:143]
	v_lshl_add_u64 v[182:183], s[16:17], 0, v[182:183]
	v_lshl_add_u64 v[182:183], v[182:183], 0, v[174:175]
	v_mov_b32_e32 v137, v33
	ds_write_b16 v226, v133 offset:2656
	v_lshlrev_b64 v[182:183], 15, v[136:137]
	v_lshl_add_u64 v[182:183], s[16:17], 0, v[182:183]
	v_cvt_pk_bf16_f32 v131, v93, s0
	v_lshl_add_u64 v[182:183], v[182:183], 0, v[174:175]
	s_mov_b64 s[22:23], 0
	ds_write_b16 v226, v131 offset:2800

.LBB0_2126:
	v_cvt_pk_bf16_f32 v135, v86, s0
	v_cvt_pk_bf16_f32 v133, v88, s0
	s_and_b64 vcc, exec, s[40:41]
	s_mov_b64 s[22:23], -1
	s_cbranch_vccnz .LBB0_2128
	v_mov_b32_e32 v131, v33
	v_lshl_add_u64 v[182:183], v[130:131], 2, v[176:177]
	flat_store_dwordx4 v[182:183], v[86:89] offset:128
	v_lshl_add_u64 v[182:183], v[168:169], 0, v[174:175]
	v_mov_b32_e32 v163, v33
	ds_write_b16 v226, v135 offset:4672
	v_lshlrev_b64 v[182:183], 15, v[162:163]
	v_lshl_add_u64 v[182:183], s[16:17], 0, v[182:183]
	v_cvt_pk_bf16_f32 v131, v87, s0
	v_lshl_add_u64 v[182:183], v[182:183], 0, v[174:175]
	v_mov_b32_e32 v153, v33
	ds_write_b16 v226, v131 offset:4816
	v_lshlrev_b64 v[182:183], 15, v[152:153]
	v_lshl_add_u64 v[182:183], s[16:17], 0, v[182:183]
	v_lshl_add_u64 v[182:183], v[182:183], 0, v[174:175]
	v_mov_b32_e32 v141, v33
	ds_write_b16 v226, v133 offset:4960
	v_lshlrev_b64 v[182:183], 15, v[140:141]
	v_lshl_add_u64 v[182:183], s[16:17], 0, v[182:183]
	v_cvt_pk_bf16_f32 v131, v89, s0
	v_lshl_add_u64 v[182:183], v[182:183], 0, v[174:175]
	s_mov_b64 s[22:23], 0
	ds_write_b16 v226, v131 offset:5104

.LBB0_2130:
	v_cvt_pk_bf16_f32 v135, v82, s0
	v_cvt_pk_bf16_f32 v133, v84, s0
	s_and_b64 vcc, exec, s[40:41]
	s_mov_b64 s[22:23], -1
	s_cbranch_vccnz .LBB0_2132
	v_mov_b32_e32 v131, v33
	v_lshl_add_u64 v[176:177], v[130:131], 2, v[176:177]
	flat_store_dwordx4 v[176:177], v[82:85] offset:192
	v_lshl_add_u64 v[176:177], v[166:167], 0, v[174:175]
	v_mov_b32_e32 v165, v33
	ds_write_b16 v226, v135 offset:6976
	v_lshlrev_b64 v[176:177], 15, v[164:165]
	v_lshl_add_u64 v[176:177], s[16:17], 0, v[176:177]
	v_cvt_pk_bf16_f32 v131, v83, s0
	v_lshl_add_u64 v[176:177], v[176:177], 0, v[174:175]
	v_mov_b32_e32 v161, v33
	ds_write_b16 v226, v131 offset:7120
	v_lshlrev_b64 v[176:177], 15, v[160:161]
	v_lshl_add_u64 v[176:177], s[16:17], 0, v[176:177]
	v_lshl_add_u64 v[176:177], v[176:177], 0, v[174:175]
	v_mov_b32_e32 v151, v33
	ds_write_b16 v226, v133 offset:7264
	v_lshlrev_b64 v[176:177], 15, v[150:151]
	v_lshl_add_u64 v[176:177], s[16:17], 0, v[176:177]
	v_cvt_pk_bf16_f32 v131, v85, s0
	v_lshl_add_u64 v[174:175], v[176:177], 0, v[174:175]
	s_mov_b64 s[22:23], 0
	ds_write_b16 v226, v131 offset:7408

.LBB0_2134:
	v_or_b32_e32 v174, 48, v148
	v_ashrrev_i32_e32 v175, 31, v174
	v_lshl_add_u64 v[176:177], s[12:13], 0, v[174:175]
	s_movk_i32 s28, 0x600
	v_mad_u64_u32 v[178:179], s[22:23], v176, s28, 0
	v_mad_i32_i24 v179, v177, s28, v179
	v_cvt_pk_bf16_f32 v137, v78, s0
	v_cvt_pk_bf16_f32 v131, v80, s0
	s_mov_b64 s[22:23], -1
	s_and_b64 vcc, exec, s[40:41]
	v_lshl_add_u64 v[176:177], s[56:57], 0, v[178:179]
	v_lshlrev_b64 v[174:175], 1, v[174:175]
	s_cbranch_vccnz .LBB0_2136
	v_mov_b32_e32 v145, v33
	v_lshlrev_b64 v[144:145], 15, v[144:145]
	v_mov_b32_e32 v139, v33
	v_mov_b32_e32 v135, v33
	v_lshl_add_u64 v[144:145], s[16:17], 0, v[144:145]
	v_lshlrev_b64 v[138:139], 15, v[138:139]
	v_lshlrev_b64 v[134:135], 15, v[134:135]
	v_lshl_add_u64 v[178:179], v[32:33], 2, v[176:177]
	v_lshl_add_u64 v[172:173], v[172:173], 0, v[174:175]
	v_cvt_pk_bf16_f32 v133, v79, s0
	v_lshl_add_u64 v[144:145], v[144:145], 0, v[174:175]
	v_lshl_add_u64 v[138:139], s[16:17], 0, v[138:139]
	v_lshl_add_u64 v[134:135], s[16:17], 0, v[134:135]
	flat_store_dwordx4 v[178:179], v[78:81]
	ds_write_b16 v226, v137 offset:96
	ds_write_b16 v226, v133 offset:240
	v_lshl_add_u64 v[138:139], v[138:139], 0, v[174:175]
	v_cvt_pk_bf16_f32 v133, v81, s0
	v_lshl_add_u64 v[134:135], v[134:135], 0, v[174:175]
	s_mov_b64 s[22:23], 0
	ds_write_b16 v226, v131 offset:384
	ds_write_b16 v226, v133 offset:528

.LBB0_2138:
	v_cvt_pk_bf16_f32 v139, v74, s0
	v_cvt_pk_bf16_f32 v138, v76, s0
	s_and_b64 vcc, exec, s[40:41]
	s_mov_b64 s[22:23], -1
	s_cbranch_vccnz .LBB0_2140
	v_mov_b32_e32 v131, v33
	v_lshl_add_u64 v[144:145], v[130:131], 2, v[176:177]
	flat_store_dwordx4 v[144:145], v[74:77] offset:64
	v_lshl_add_u64 v[144:145], v[170:171], 0, v[174:175]
	v_mov_b32_e32 v159, v33
	ds_write_b16 v226, v139 offset:2400
	v_lshlrev_b64 v[144:145], 15, v[158:159]
	v_mov_b32_e32 v143, v33
	v_mov_b32_e32 v137, v33
	v_lshl_add_u64 v[144:145], s[16:17], 0, v[144:145]
	v_lshlrev_b64 v[142:143], 15, v[142:143]
	v_lshlrev_b64 v[136:137], 15, v[136:137]
	v_cvt_pk_bf16_f32 v32, v75, s0
	v_lshl_add_u64 v[144:145], v[144:145], 0, v[174:175]
	v_lshl_add_u64 v[142:143], s[16:17], 0, v[142:143]
	v_lshl_add_u64 v[136:137], s[16:17], 0, v[136:137]
	ds_write_b16 v226, v32 offset:2544
	v_lshl_add_u64 v[142:143], v[142:143], 0, v[174:175]
	v_cvt_pk_bf16_f32 v32, v77, s0
	v_lshl_add_u64 v[136:137], v[136:137], 0, v[174:175]
	s_mov_b64 s[22:23], 0
	ds_write_b16 v226, v138 offset:2688
	ds_write_b16 v226, v32 offset:2832

.LBB0_2142:
	v_cvt_pk_bf16_f32 v137, v70, s0
	v_cvt_pk_bf16_f32 v136, v72, s0
	s_and_b64 vcc, exec, s[40:41]
	s_mov_b64 s[22:23], -1
	s_cbranch_vccnz .LBB0_2144
	v_mov_b32_e32 v131, v33
	v_lshl_add_u64 v[138:139], v[130:131], 2, v[176:177]
	flat_store_dwordx4 v[138:139], v[70:73] offset:128
	v_lshl_add_u64 v[138:139], v[168:169], 0, v[174:175]
	v_mov_b32_e32 v163, v33
	ds_write_b16 v226, v137 offset:4704
	v_lshlrev_b64 v[138:139], 15, v[162:163]
	v_lshl_add_u64 v[138:139], s[16:17], 0, v[138:139]
	v_cvt_pk_bf16_f32 v32, v71, s0
	v_lshl_add_u64 v[138:139], v[138:139], 0, v[174:175]
	v_mov_b32_e32 v153, v33
	ds_write_b16 v226, v32 offset:4848
	v_lshlrev_b64 v[138:139], 15, v[152:153]
	v_lshl_add_u64 v[138:139], s[16:17], 0, v[138:139]
	v_lshl_add_u64 v[138:139], v[138:139], 0, v[174:175]
	v_mov_b32_e32 v141, v33
	ds_write_b16 v226, v136 offset:4992
	v_lshlrev_b64 v[138:139], 15, v[140:141]
	v_lshl_add_u64 v[138:139], s[16:17], 0, v[138:139]
	v_cvt_pk_bf16_f32 v32, v73, s0
	v_lshl_add_u64 v[138:139], v[138:139], 0, v[174:175]
	s_mov_b64 s[22:23], 0
	ds_write_b16 v226, v32 offset:5136

.LBB0_2146:
	v_cvt_pk_bf16_f32 v137, v66, s0
	v_cvt_pk_bf16_f32 v136, v68, s0
	s_and_b64 vcc, exec, s[40:41]
	s_mov_b64 s[22:23], -1
	s_cbranch_vccnz .LBB0_2148
	v_mov_b32_e32 v131, v33
	v_lshl_add_u64 v[138:139], v[130:131], 2, v[176:177]
	flat_store_dwordx4 v[138:139], v[66:69] offset:192
	v_lshl_add_u64 v[138:139], v[166:167], 0, v[174:175]
	v_mov_b32_e32 v165, v33
	ds_write_b16 v226, v137 offset:7008
	v_lshlrev_b64 v[138:139], 15, v[164:165]
	v_lshl_add_u64 v[138:139], s[16:17], 0, v[138:139]
	v_cvt_pk_bf16_f32 v32, v67, s0
	v_lshl_add_u64 v[138:139], v[138:139], 0, v[174:175]
	v_mov_b32_e32 v161, v33
	ds_write_b16 v226, v32 offset:7152
	v_lshlrev_b64 v[138:139], 15, v[160:161]
	v_lshl_add_u64 v[138:139], s[16:17], 0, v[138:139]
	v_lshl_add_u64 v[138:139], v[138:139], 0, v[174:175]
	v_mov_b32_e32 v151, v33
	ds_write_b16 v226, v136 offset:7296
	v_lshlrev_b64 v[138:139], 15, v[150:151]
	v_lshl_add_u64 v[138:139], s[16:17], 0, v[138:139]
	v_cvt_pk_bf16_f32 v32, v69, s0
	v_lshl_add_u64 v[138:139], v[138:139], 0, v[174:175]
	s_mov_b64 s[22:23], 0
	ds_write_b16 v226, v32 offset:7440

.LBB0_2276:
	s_andn2_saveexec_b64 s[22:23], s[40:41]
	s_cbranch_execz .LBB0_2341
	v_subrev_u32_e32 v112, 37, v206
	v_lshlrev_b32_e32 v80, 6, v112
	v_ashrrev_i32_e32 v149, 31, v148
	v_lshlrev_b64 v[68:69], 10, v[148:149]
	v_or_b32_e32 v32, v80, v147
	v_cndmask_b32_e64 v70, 0, 1, s[42:43]
	v_cvt_pk_bf16_f32 v67, v62, s0
	v_cvt_pk_bf16_f32 v66, v64, s0
	s_mov_b64 s[28:29], -1
	v_cmp_ne_u32_e64 s[40:41], 1, v70
	s_andn2_b64 vcc, exec, s[42:43]
	v_lshl_add_u64 v[98:99], s[46:47], 0, v[68:69]
	v_lshlrev_b64 v[92:93], 15, v[32:33]
	v_lshl_add_u64 v[96:97], v[148:149], 1, s[8:9]
	v_or_b32_e32 v78, 1, v32
	v_or_b32_e32 v72, 2, v32
	v_or_b32_e32 v68, 3, v32
	s_cbranch_vccnz .LBB0_2279
	v_lshl_add_u64 v[70:71], v[32:33], 2, v[98:99]
	flat_store_dwordx4 v[70:71], v[62:65]
	v_lshl_add_u64 v[70:71], v[96:97], 0, v[92:93]
	v_mov_b32_e32 v79, v33
	v_lshrrev_b32_e32 v226, 6, v186
	v_mul_u32_u24_e32 v226, 0x4400, v226
	v_bfe_u32 v227, v186, 4, 2
	v_mul_u32_u24_e32 v230, 0x240, v227
	v_add_u32_e32 v226, v226, v230
	v_and_b32_e32 v230, 15, v186
	v_lshl_add_u32 v226, v230, 1, v226
	v_mov_b32_e32 v228, v70
	v_mov_b32_e32 v229, v71
	v_and_b32_e32 v231, 7, v230
	v_lshlrev_b32_e32 v231, 4, v231
	v_lshlrev_b32_e32 v234, 1, v230
	v_sub_u32_e32 v231, v231, v234
	v_lshrrev_b32_e32 v234, 3, v230
	v_lshl_add_u32 v231, v234, 15, v231
	v_lshlrev_b32_e32 v234, 16, v227
	v_sub_u32_e32 v234, v231, v234
	v_ashrrev_i32_e32 v235, 31, v234
	v_lshl_add_u64 v[228:229], v[228:229], 0, v[234:235]
	v_mov_b32_e32 v232, 0x40000
	v_mov_b32_e32 v233, 0
	ds_write_b16 v226, v67 offset:0
	v_lshlrev_b64 v[70:71], 15, v[78:79]
	v_cvt_pk_bf16_f32 v69, v63, s0
	v_lshl_add_u64 v[70:71], v[96:97], 0, v[70:71]
	v_mov_b32_e32 v73, v33
	ds_write_b16 v226, v69 offset:144
	v_lshlrev_b64 v[70:71], 15, v[72:73]
	v_lshl_add_u64 v[70:71], v[96:97], 0, v[70:71]
	v_mov_b32_e32 v69, v33
	ds_write_b16 v226, v66 offset:288
	v_lshlrev_b64 v[70:71], 15, v[68:69]
	v_cvt_pk_bf16_f32 v73, v65, s0
	v_lshl_add_u64 v[70:71], v[96:97], 0, v[70:71]
	s_mov_b64 s[28:29], 0
	ds_write_b16 v226, v73 offset:432

.LBB0_2281:
	v_or_b32_e32 v113, 16, v147
	v_or_b32_e32 v70, v80, v113
	v_mov_b32_e32 v71, v33
	v_cvt_pk_bf16_f32 v73, v58, s0
	v_cvt_pk_bf16_f32 v69, v60, s0
	s_mov_b64 s[28:29], -1
	s_and_b64 vcc, exec, s[40:41]
	v_add_u32_e32 v66, v80, v147
	v_lshlrev_b64 v[94:95], 15, v[70:71]
	v_or_b32_e32 v84, 1, v70
	v_or_b32_e32 v76, 2, v70
	v_or_b32_e32 v70, 3, v70
	s_cbranch_vccnz .LBB0_2283
	v_mov_b32_e32 v67, v33
	v_lshl_add_u64 v[74:75], v[66:67], 2, v[98:99]
	flat_store_dwordx4 v[74:75], v[58:61] offset:64
	v_lshl_add_u64 v[74:75], v[96:97], 0, v[94:95]
	v_mov_b32_e32 v85, v33
	ds_write_b16 v226, v73 offset:2304
	v_lshlrev_b64 v[74:75], 15, v[84:85]
	v_cvt_pk_bf16_f32 v67, v59, s0
	v_lshl_add_u64 v[74:75], v[96:97], 0, v[74:75]
	v_mov_b32_e32 v77, v33
	ds_write_b16 v226, v67 offset:2448
	v_lshlrev_b64 v[74:75], 15, v[76:77]
	v_lshl_add_u64 v[74:75], v[96:97], 0, v[74:75]
	v_mov_b32_e32 v71, v33
	ds_write_b16 v226, v69 offset:2592
	v_lshlrev_b64 v[74:75], 15, v[70:71]
	v_cvt_pk_bf16_f32 v67, v61, s0
	v_lshl_add_u64 v[74:75], v[96:97], 0, v[74:75]
	s_mov_b64 s[28:29], 0
	ds_write_b16 v226, v67 offset:2736

.LBB0_2285:
	v_or_b32_e32 v114, 32, v147
	v_or_b32_e32 v74, v80, v114
	v_mov_b32_e32 v75, v33
	v_cvt_pk_bf16_f32 v71, v54, s0
	v_cvt_pk_bf16_f32 v69, v56, s0
	s_mov_b64 s[28:29], -1
	s_and_b64 vcc, exec, s[40:41]
	v_lshlrev_b64 v[100:101], 15, v[74:75]
	v_or_b32_e32 v88, 1, v74
	v_or_b32_e32 v82, 2, v74
	v_or_b32_e32 v74, 3, v74
	s_cbranch_vccnz .LBB0_2287
	v_mov_b32_e32 v67, v33
	v_lshl_add_u64 v[86:87], v[66:67], 2, v[98:99]
	flat_store_dwordx4 v[86:87], v[54:57] offset:128
	v_lshl_add_u64 v[86:87], v[96:97], 0, v[100:101]
	v_mov_b32_e32 v89, v33
	ds_write_b16 v226, v71 offset:4608
	v_lshlrev_b64 v[86:87], 15, v[88:89]
	v_cvt_pk_bf16_f32 v67, v55, s0
	v_lshl_add_u64 v[86:87], v[96:97], 0, v[86:87]
	v_mov_b32_e32 v83, v33
	ds_write_b16 v226, v67 offset:4752
	v_lshlrev_b64 v[86:87], 15, v[82:83]
	v_lshl_add_u64 v[86:87], v[96:97], 0, v[86:87]
	v_mov_b32_e32 v75, v33
	ds_write_b16 v226, v69 offset:4896
	v_lshlrev_b64 v[86:87], 15, v[74:75]
	v_cvt_pk_bf16_f32 v67, v57, s0
	v_lshl_add_u64 v[86:87], v[96:97], 0, v[86:87]
	s_mov_b64 s[28:29], 0
	ds_write_b16 v226, v67 offset:5040

.LBB0_2289:
	v_or_b32_e32 v115, 48, v147
	v_or_b32_e32 v80, v80, v115
	v_mov_b32_e32 v81, v33
	v_cvt_pk_bf16_f32 v71, v50, s0
	v_cvt_pk_bf16_f32 v69, v52, s0
	s_mov_b64 s[28:29], -1
	s_and_b64 vcc, exec, s[40:41]
	v_lshlrev_b64 v[102:103], 15, v[80:81]
	v_or_b32_e32 v90, 1, v80
	v_or_b32_e32 v86, 2, v80
	v_or_b32_e32 v80, 3, v80
	s_cbranch_vccnz .LBB0_2291
	v_mov_b32_e32 v67, v33
	v_lshl_add_u64 v[98:99], v[66:67], 2, v[98:99]
	flat_store_dwordx4 v[98:99], v[50:53] offset:192
	v_lshl_add_u64 v[98:99], v[96:97], 0, v[102:103]
	v_mov_b32_e32 v91, v33
	ds_write_b16 v226, v71 offset:6912
	v_lshlrev_b64 v[98:99], 15, v[90:91]
	v_cvt_pk_bf16_f32 v67, v51, s0
	v_lshl_add_u64 v[98:99], v[96:97], 0, v[98:99]
	v_mov_b32_e32 v87, v33
	ds_write_b16 v226, v67 offset:7056
	v_lshlrev_b64 v[98:99], 15, v[86:87]
	v_lshl_add_u64 v[98:99], v[96:97], 0, v[98:99]
	v_mov_b32_e32 v81, v33
	ds_write_b16 v226, v69 offset:7200
	v_lshlrev_b64 v[98:99], 15, v[80:81]
	v_cvt_pk_bf16_f32 v67, v53, s0
	v_lshl_add_u64 v[96:97], v[96:97], 0, v[98:99]
	s_mov_b64 s[28:29], 0
	ds_write_b16 v226, v67 offset:7344

.LBB0_2293:
	v_or_b32_e32 v96, 16, v148
	v_ashrrev_i32_e32 v97, 31, v96
	v_lshlrev_b64 v[98:99], 10, v[96:97]
	v_cvt_pk_bf16_f32 v71, v46, s0
	v_cvt_pk_bf16_f32 v67, v48, s0
	s_mov_b64 s[28:29], -1
	s_and_b64 vcc, exec, s[40:41]
	v_lshl_add_u64 v[108:109], s[46:47], 0, v[98:99]
	v_lshlrev_b64 v[104:105], 1, v[96:97]
	v_lshl_add_u64 v[98:99], s[8:9], 0, v[92:93]
	s_cbranch_vccnz .LBB0_2295
	v_lshl_add_u64 v[92:93], v[32:33], 2, v[108:109]
	flat_store_dwordx4 v[92:93], v[46:49]
	v_lshl_add_u64 v[92:93], v[98:99], 0, v[104:105]
	v_mov_b32_e32 v79, v33
	ds_write_b16 v226, v71 offset:32
	v_lshlrev_b64 v[92:93], 15, v[78:79]
	v_lshl_add_u64 v[92:93], s[8:9], 0, v[92:93]
	v_cvt_pk_bf16_f32 v69, v47, s0
	v_lshl_add_u64 v[92:93], v[92:93], 0, v[104:105]
	v_mov_b32_e32 v73, v33
	ds_write_b16 v226, v69 offset:176
	v_lshlrev_b64 v[92:93], 15, v[72:73]
	v_lshl_add_u64 v[92:93], s[8:9], 0, v[92:93]
	v_lshl_add_u64 v[92:93], v[92:93], 0, v[104:105]
	v_mov_b32_e32 v69, v33
	ds_write_b16 v226, v67 offset:320
	v_lshlrev_b64 v[92:93], 15, v[68:69]
	v_lshl_add_u64 v[92:93], s[8:9], 0, v[92:93]
	v_cvt_pk_bf16_f32 v73, v49, s0
	v_lshl_add_u64 v[92:93], v[92:93], 0, v[104:105]
	s_mov_b64 s[28:29], 0
	ds_write_b16 v226, v73 offset:464

.LBB0_2297:
	v_cvt_pk_bf16_f32 v73, v42, s0
	v_cvt_pk_bf16_f32 v69, v44, s0
	s_mov_b64 s[28:29], -1
	s_and_b64 vcc, exec, s[40:41]
	v_lshl_add_u64 v[96:97], s[8:9], 0, v[94:95]
	s_cbranch_vccnz .LBB0_2299
	v_mov_b32_e32 v67, v33
	v_lshl_add_u64 v[92:93], v[66:67], 2, v[108:109]
	flat_store_dwordx4 v[92:93], v[42:45] offset:64
	v_lshl_add_u64 v[92:93], v[96:97], 0, v[104:105]
	v_mov_b32_e32 v85, v33
	ds_write_b16 v226, v73 offset:2336
	v_lshlrev_b64 v[92:93], 15, v[84:85]
	v_lshl_add_u64 v[92:93], s[8:9], 0, v[92:93]
	v_cvt_pk_bf16_f32 v67, v43, s0
	v_lshl_add_u64 v[92:93], v[92:93], 0, v[104:105]
	v_mov_b32_e32 v77, v33
	ds_write_b16 v226, v67 offset:2480
	v_lshlrev_b64 v[92:93], 15, v[76:77]
	v_lshl_add_u64 v[92:93], s[8:9], 0, v[92:93]
	v_lshl_add_u64 v[92:93], v[92:93], 0, v[104:105]
	v_mov_b32_e32 v71, v33
	ds_write_b16 v226, v69 offset:2624
	v_lshlrev_b64 v[92:93], 15, v[70:71]
	v_lshl_add_u64 v[92:93], s[8:9], 0, v[92:93]
	v_cvt_pk_bf16_f32 v67, v45, s0
	v_lshl_add_u64 v[92:93], v[92:93], 0, v[104:105]
	s_mov_b64 s[28:29], 0
	ds_write_b16 v226, v67 offset:2768

.LBB0_2301:
	v_cvt_pk_bf16_f32 v71, v38, s0
	v_cvt_pk_bf16_f32 v69, v40, s0
	s_mov_b64 s[28:29], -1
	s_and_b64 vcc, exec, s[40:41]
	v_lshl_add_u64 v[94:95], s[8:9], 0, v[100:101]
	s_cbranch_vccnz .LBB0_2303
	v_mov_b32_e32 v67, v33
	v_lshl_add_u64 v[92:93], v[66:67], 2, v[108:109]
	flat_store_dwordx4 v[92:93], v[38:41] offset:128
	v_lshl_add_u64 v[92:93], v[94:95], 0, v[104:105]
	v_mov_b32_e32 v89, v33
	ds_write_b16 v226, v71 offset:4640
	v_lshlrev_b64 v[92:93], 15, v[88:89]
	v_lshl_add_u64 v[92:93], s[8:9], 0, v[92:93]
	v_cvt_pk_bf16_f32 v67, v39, s0
	v_lshl_add_u64 v[92:93], v[92:93], 0, v[104:105]
	v_mov_b32_e32 v83, v33
	ds_write_b16 v226, v67 offset:4784
	v_lshlrev_b64 v[92:93], 15, v[82:83]
	v_lshl_add_u64 v[92:93], s[8:9], 0, v[92:93]
	v_lshl_add_u64 v[92:93], v[92:93], 0, v[104:105]
	v_mov_b32_e32 v75, v33
	ds_write_b16 v226, v69 offset:4928
	v_lshlrev_b64 v[92:93], 15, v[74:75]
	v_lshl_add_u64 v[92:93], s[8:9], 0, v[92:93]
	v_cvt_pk_bf16_f32 v67, v41, s0
	v_lshl_add_u64 v[92:93], v[92:93], 0, v[104:105]
	s_mov_b64 s[28:29], 0
	ds_write_b16 v226, v67 offset:5072

.LBB0_2305:
	v_cvt_pk_bf16_f32 v71, v34, s0
	v_cvt_pk_bf16_f32 v69, v36, s0
	s_mov_b64 s[28:29], -1
	s_and_b64 vcc, exec, s[40:41]
	v_lshl_add_u64 v[92:93], s[8:9], 0, v[102:103]
	s_cbranch_vccnz .LBB0_2307
	v_mov_b32_e32 v67, v33
	v_lshl_add_u64 v[100:101], v[66:67], 2, v[108:109]
	flat_store_dwordx4 v[100:101], v[34:37] offset:192
	v_lshl_add_u64 v[100:101], v[92:93], 0, v[104:105]
	v_mov_b32_e32 v91, v33
	ds_write_b16 v226, v71 offset:6944
	v_lshlrev_b64 v[100:101], 15, v[90:91]
	v_lshl_add_u64 v[100:101], s[8:9], 0, v[100:101]
	v_cvt_pk_bf16_f32 v67, v35, s0
	v_lshl_add_u64 v[100:101], v[100:101], 0, v[104:105]
	v_mov_b32_e32 v87, v33
	ds_write_b16 v226, v67 offset:7088
	v_lshlrev_b64 v[100:101], 15, v[86:87]
	v_lshl_add_u64 v[100:101], s[8:9], 0, v[100:101]
	v_lshl_add_u64 v[100:101], v[100:101], 0, v[104:105]
	v_mov_b32_e32 v81, v33
	ds_write_b16 v226, v69 offset:7232
	v_lshlrev_b64 v[100:101], 15, v[80:81]
	v_lshl_add_u64 v[100:101], s[8:9], 0, v[100:101]
	v_cvt_pk_bf16_f32 v67, v37, s0
	v_lshl_add_u64 v[100:101], v[100:101], 0, v[104:105]
	s_mov_b64 s[28:29], 0
	ds_write_b16 v226, v67 offset:7376

.LBB0_2309:
	v_or_b32_e32 v100, 32, v148
	v_ashrrev_i32_e32 v101, 31, v100
	v_lshlrev_b64 v[102:103], 10, v[100:101]
	v_cvt_pk_bf16_f32 v71, v28, s0
	v_cvt_pk_bf16_f32 v67, v30, s0
	s_mov_b64 s[28:29], -1
	s_and_b64 vcc, exec, s[40:41]
	v_lshl_add_u64 v[104:105], s[46:47], 0, v[102:103]
	v_lshlrev_b64 v[100:101], 1, v[100:101]
	s_cbranch_vccnz .LBB0_2311
	v_lshl_add_u64 v[102:103], v[32:33], 2, v[104:105]
	flat_store_dwordx4 v[102:103], v[28:31]
	v_lshl_add_u64 v[102:103], v[98:99], 0, v[100:101]
	v_mov_b32_e32 v79, v33
	ds_write_b16 v226, v71 offset:64
	v_lshlrev_b64 v[102:103], 15, v[78:79]
	v_lshl_add_u64 v[102:103], s[8:9], 0, v[102:103]
	v_cvt_pk_bf16_f32 v69, v29, s0
	v_lshl_add_u64 v[102:103], v[102:103], 0, v[100:101]
	v_mov_b32_e32 v73, v33
	ds_write_b16 v226, v69 offset:208
	v_lshlrev_b64 v[102:103], 15, v[72:73]
	v_lshl_add_u64 v[102:103], s[8:9], 0, v[102:103]
	v_lshl_add_u64 v[102:103], v[102:103], 0, v[100:101]
	v_mov_b32_e32 v69, v33
	ds_write_b16 v226, v67 offset:352
	v_lshlrev_b64 v[102:103], 15, v[68:69]
	v_lshl_add_u64 v[102:103], s[8:9], 0, v[102:103]
	v_cvt_pk_bf16_f32 v73, v31, s0
	v_lshl_add_u64 v[102:103], v[102:103], 0, v[100:101]
	s_mov_b64 s[28:29], 0
	ds_write_b16 v226, v73 offset:496

.LBB0_2313:
	v_cvt_pk_bf16_f32 v73, v24, s0
	v_cvt_pk_bf16_f32 v69, v26, s0
	s_and_b64 vcc, exec, s[40:41]
	s_mov_b64 s[28:29], -1
	s_cbranch_vccnz .LBB0_2315
	v_mov_b32_e32 v67, v33
	v_lshl_add_u64 v[108:109], v[66:67], 2, v[104:105]
	flat_store_dwordx4 v[108:109], v[24:27] offset:64
	v_lshl_add_u64 v[108:109], v[96:97], 0, v[100:101]
	v_mov_b32_e32 v85, v33
	ds_write_b16 v226, v73 offset:2368
	v_lshlrev_b64 v[108:109], 15, v[84:85]
	v_lshl_add_u64 v[108:109], s[8:9], 0, v[108:109]
	v_cvt_pk_bf16_f32 v67, v25, s0
	v_lshl_add_u64 v[108:109], v[108:109], 0, v[100:101]
	v_mov_b32_e32 v77, v33
	ds_write_b16 v226, v67 offset:2512
	v_lshlrev_b64 v[108:109], 15, v[76:77]
	v_lshl_add_u64 v[108:109], s[8:9], 0, v[108:109]
	v_lshl_add_u64 v[108:109], v[108:109], 0, v[100:101]
	v_mov_b32_e32 v71, v33
	ds_write_b16 v226, v69 offset:2656
	v_lshlrev_b64 v[108:109], 15, v[70:71]
	v_lshl_add_u64 v[108:109], s[8:9], 0, v[108:109]
	v_cvt_pk_bf16_f32 v67, v27, s0
	v_lshl_add_u64 v[108:109], v[108:109], 0, v[100:101]
	s_mov_b64 s[28:29], 0
	ds_write_b16 v226, v67 offset:2800

.LBB0_2317:
	v_cvt_pk_bf16_f32 v71, v20, s0
	v_cvt_pk_bf16_f32 v69, v22, s0
	s_and_b64 vcc, exec, s[40:41]
	s_mov_b64 s[28:29], -1
	s_cbranch_vccnz .LBB0_2319
	v_mov_b32_e32 v67, v33
	v_lshl_add_u64 v[108:109], v[66:67], 2, v[104:105]
	flat_store_dwordx4 v[108:109], v[20:23] offset:128
	v_lshl_add_u64 v[108:109], v[94:95], 0, v[100:101]
	v_mov_b32_e32 v89, v33
	ds_write_b16 v226, v71 offset:4672
	v_lshlrev_b64 v[108:109], 15, v[88:89]
	v_lshl_add_u64 v[108:109], s[8:9], 0, v[108:109]
	v_cvt_pk_bf16_f32 v67, v21, s0
	v_lshl_add_u64 v[108:109], v[108:109], 0, v[100:101]
	v_mov_b32_e32 v83, v33
	ds_write_b16 v226, v67 offset:4816
	v_lshlrev_b64 v[108:109], 15, v[82:83]
	v_lshl_add_u64 v[108:109], s[8:9], 0, v[108:109]
	v_lshl_add_u64 v[108:109], v[108:109], 0, v[100:101]
	v_mov_b32_e32 v75, v33
	ds_write_b16 v226, v69 offset:4960
	v_lshlrev_b64 v[108:109], 15, v[74:75]
	v_lshl_add_u64 v[108:109], s[8:9], 0, v[108:109]
	v_cvt_pk_bf16_f32 v67, v23, s0
	v_lshl_add_u64 v[108:109], v[108:109], 0, v[100:101]
	s_mov_b64 s[28:29], 0
	ds_write_b16 v226, v67 offset:5104

.LBB0_2321:
	v_cvt_pk_bf16_f32 v71, v16, s0
	v_cvt_pk_bf16_f32 v69, v18, s0
	s_and_b64 vcc, exec, s[40:41]
	s_mov_b64 s[28:29], -1
	s_cbranch_vccnz .LBB0_2323
	v_mov_b32_e32 v67, v33
	v_lshl_add_u64 v[104:105], v[66:67], 2, v[104:105]
	flat_store_dwordx4 v[104:105], v[16:19] offset:192
	v_lshl_add_u64 v[104:105], v[92:93], 0, v[100:101]
	v_mov_b32_e32 v91, v33
	ds_write_b16 v226, v71 offset:6976
	v_lshlrev_b64 v[104:105], 15, v[90:91]
	v_lshl_add_u64 v[104:105], s[8:9], 0, v[104:105]
	v_cvt_pk_bf16_f32 v67, v17, s0
	v_lshl_add_u64 v[104:105], v[104:105], 0, v[100:101]
	v_mov_b32_e32 v87, v33
	ds_write_b16 v226, v67 offset:7120
	v_lshlrev_b64 v[104:105], 15, v[86:87]
	v_lshl_add_u64 v[104:105], s[8:9], 0, v[104:105]
	v_lshl_add_u64 v[104:105], v[104:105], 0, v[100:101]
	v_mov_b32_e32 v81, v33
	ds_write_b16 v226, v69 offset:7264
	v_lshlrev_b64 v[104:105], 15, v[80:81]
	v_lshl_add_u64 v[104:105], s[8:9], 0, v[104:105]
	v_cvt_pk_bf16_f32 v67, v19, s0
	v_lshl_add_u64 v[100:101], v[104:105], 0, v[100:101]
	s_mov_b64 s[28:29], 0
	ds_write_b16 v226, v67 offset:7408

.LBB0_2325:
	v_or_b32_e32 v100, 48, v148
	v_ashrrev_i32_e32 v101, 31, v100
	v_lshlrev_b64 v[102:103], 10, v[100:101]
	v_cvt_pk_bf16_f32 v71, v12, s0
	v_cvt_pk_bf16_f32 v67, v14, s0
	s_mov_b64 s[28:29], -1
	s_and_b64 vcc, exec, s[40:41]
	v_lshl_add_u64 v[102:103], s[46:47], 0, v[102:103]
	v_lshlrev_b64 v[100:101], 1, v[100:101]
	s_cbranch_vccnz .LBB0_2327
	v_mov_b32_e32 v79, v33
	v_lshlrev_b64 v[78:79], 15, v[78:79]
	v_lshl_add_u64 v[78:79], s[8:9], 0, v[78:79]
	v_lshl_add_u64 v[104:105], v[32:33], 2, v[102:103]
	v_lshl_add_u64 v[98:99], v[98:99], 0, v[100:101]
	v_cvt_pk_bf16_f32 v69, v13, s0
	v_lshl_add_u64 v[78:79], v[78:79], 0, v[100:101]
	v_mov_b32_e32 v73, v33
	flat_store_dwordx4 v[104:105], v[12:15]
	ds_write_b16 v226, v71 offset:96
	ds_write_b16 v226, v69 offset:240
	v_lshlrev_b64 v[72:73], 15, v[72:73]
	v_mov_b32_e32 v69, v33
	v_lshl_add_u64 v[72:73], s[8:9], 0, v[72:73]
	v_lshlrev_b64 v[68:69], 15, v[68:69]
	v_lshl_add_u64 v[72:73], v[72:73], 0, v[100:101]
	v_lshl_add_u64 v[68:69], s[8:9], 0, v[68:69]
	ds_write_b16 v226, v67 offset:384
	v_cvt_pk_bf16_f32 v72, v15, s0
	v_lshl_add_u64 v[68:69], v[68:69], 0, v[100:101]
	s_mov_b64 s[28:29], 0
	ds_write_b16 v226, v72 offset:528

.LBB0_2329:
	v_cvt_pk_bf16_f32 v78, v8, s0
	v_cvt_pk_bf16_f32 v75, v10, s0
	s_and_b64 vcc, exec, s[40:41]
	s_mov_b64 s[28:29], -1
	s_cbranch_vccnz .LBB0_2331
	v_mov_b32_e32 v85, v33
	v_lshlrev_b64 v[84:85], 15, v[84:85]
	v_mov_b32_e32 v77, v33
	v_mov_b32_e32 v71, v33
	v_mov_b32_e32 v67, v33
	v_lshl_add_u64 v[84:85], s[8:9], 0, v[84:85]
	v_lshlrev_b64 v[76:77], 15, v[76:77]
	v_lshlrev_b64 v[70:71], 15, v[70:71]
	v_lshl_add_u64 v[98:99], v[66:67], 2, v[102:103]
	v_lshl_add_u64 v[96:97], v[96:97], 0, v[100:101]
	v_cvt_pk_bf16_f32 v32, v9, s0
	v_lshl_add_u64 v[84:85], v[84:85], 0, v[100:101]
	v_lshl_add_u64 v[76:77], s[8:9], 0, v[76:77]
	v_lshl_add_u64 v[70:71], s[8:9], 0, v[70:71]
	flat_store_dwordx4 v[98:99], v[8:11] offset:64
	ds_write_b16 v226, v78 offset:2400
	ds_write_b16 v226, v32 offset:2544
	v_lshl_add_u64 v[76:77], v[76:77], 0, v[100:101]
	v_cvt_pk_bf16_f32 v32, v11, s0
	v_lshl_add_u64 v[70:71], v[70:71], 0, v[100:101]
	s_mov_b64 s[28:29], 0
	ds_write_b16 v226, v75 offset:2688
	ds_write_b16 v226, v32 offset:2832

.LBB0_2333:
	v_cvt_pk_bf16_f32 v71, v4, s0
	v_cvt_pk_bf16_f32 v70, v6, s0
	s_and_b64 vcc, exec, s[40:41]
	s_mov_b64 s[28:29], -1
	s_cbranch_vccnz .LBB0_2335
	v_mov_b32_e32 v67, v33
	v_lshl_add_u64 v[76:77], v[66:67], 2, v[102:103]
	flat_store_dwordx4 v[76:77], v[4:7] offset:128
	v_lshl_add_u64 v[76:77], v[94:95], 0, v[100:101]
	v_mov_b32_e32 v89, v33
	ds_write_b16 v226, v71 offset:4704
	v_lshlrev_b64 v[76:77], 15, v[88:89]
	v_lshl_add_u64 v[76:77], s[8:9], 0, v[76:77]
	v_cvt_pk_bf16_f32 v32, v5, s0
	v_lshl_add_u64 v[76:77], v[76:77], 0, v[100:101]
	v_mov_b32_e32 v83, v33
	v_mov_b32_e32 v75, v33
	ds_write_b16 v226, v32 offset:4848
	v_lshlrev_b64 v[76:77], 15, v[82:83]
	v_lshlrev_b64 v[74:75], 15, v[74:75]
	v_lshl_add_u64 v[76:77], s[8:9], 0, v[76:77]
	v_lshl_add_u64 v[74:75], s[8:9], 0, v[74:75]
	v_lshl_add_u64 v[76:77], v[76:77], 0, v[100:101]
	v_cvt_pk_bf16_f32 v32, v7, s0
	v_lshl_add_u64 v[74:75], v[74:75], 0, v[100:101]
	s_mov_b64 s[28:29], 0
	ds_write_b16 v226, v70 offset:4992
	ds_write_b16 v226, v32 offset:5136

.LBB0_2337:
	v_cvt_pk_bf16_f32 v71, v0, s0
	v_cvt_pk_bf16_f32 v70, v2, s0
	s_and_b64 vcc, exec, s[40:41]
	s_mov_b64 s[28:29], -1
	s_cbranch_vccnz .LBB0_2339
	v_mov_b32_e32 v67, v33
	v_lshl_add_u64 v[74:75], v[66:67], 2, v[102:103]
	flat_store_dwordx4 v[74:75], v[0:3] offset:192
	v_lshl_add_u64 v[74:75], v[92:93], 0, v[100:101]
	v_mov_b32_e32 v91, v33
	ds_write_b16 v226, v71 offset:7008
	v_lshlrev_b64 v[74:75], 15, v[90:91]
	v_lshl_add_u64 v[74:75], s[8:9], 0, v[74:75]
	v_cvt_pk_bf16_f32 v32, v1, s0
	v_lshl_add_u64 v[74:75], v[74:75], 0, v[100:101]
	v_mov_b32_e32 v87, v33
	ds_write_b16 v226, v32 offset:7152
	v_lshlrev_b64 v[74:75], 15, v[86:87]
	v_lshl_add_u64 v[74:75], s[8:9], 0, v[74:75]
	v_lshl_add_u64 v[74:75], v[74:75], 0, v[100:101]
	v_mov_b32_e32 v81, v33
	ds_write_b16 v226, v70 offset:7296
	v_lshlrev_b64 v[74:75], 15, v[80:81]
	v_lshl_add_u64 v[74:75], s[8:9], 0, v[74:75]
	v_cvt_pk_bf16_f32 v32, v3, s0
	v_lshl_add_u64 v[74:75], v[74:75], 0, v[100:101]
	s_mov_b64 s[28:29], 0
	ds_write_b16 v226, v32 offset:7440

.LBB0_2411:
	s_andn2_saveexec_b64 s[0:1], s[66:67]
	s_cbranch_execz .LBB0_2476
	v_ashrrev_i32_e32 v149, 31, v148
	v_subrev_u32_e32 v70, 23, v206
	v_lshl_add_u64 v[66:67], s[12:13], 0, v[148:149]
	s_movk_i32 s28, 0x600
	v_lshlrev_b32_e32 v71, 6, v70
	v_mad_u64_u32 v[72:73], s[22:23], v66, s28, 0
	v_mad_i32_i24 v73, v67, s28, v73
	v_or_b32_e32 v32, v71, v147
	v_cndmask_b32_e64 v66, 0, 1, s[42:43]
	v_cvt_pk_bf16_f32 v69, v62, s0
	v_cvt_pk_bf16_f32 v68, v64, s0
	s_mov_b64 s[22:23], -1
	v_cmp_ne_u32_e64 s[40:41], 1, v66
	s_andn2_b64 vcc, exec, s[42:43]
	v_lshl_add_u64 v[102:103], s[56:57], 0, v[72:73]
	v_lshlrev_b64 v[96:97], 15, v[32:33]
	v_lshl_add_u64 v[100:101], v[148:149], 1, s[16:17]
	v_or_b32_e32 v82, 1, v32
	v_or_b32_e32 v76, 2, v32
	v_or_b32_e32 v72, 3, v32
	s_cbranch_vccnz .LBB0_2414
	v_lshl_add_u64 v[66:67], v[32:33], 2, v[102:103]
	flat_store_dwordx4 v[66:67], v[62:65]
	v_lshl_add_u64 v[66:67], v[100:101], 0, v[96:97]
	v_mov_b32_e32 v83, v33
	v_lshrrev_b32_e32 v226, 6, v186
	v_mul_u32_u24_e32 v226, 0x4400, v226
	v_bfe_u32 v227, v186, 4, 2
	v_mul_u32_u24_e32 v230, 0x240, v227
	v_add_u32_e32 v226, v226, v230
	v_and_b32_e32 v230, 15, v186
	v_lshl_add_u32 v226, v230, 1, v226
	v_mov_b32_e32 v228, v66
	v_mov_b32_e32 v229, v67
	v_and_b32_e32 v231, 7, v230
	v_lshlrev_b32_e32 v231, 4, v231
	v_lshlrev_b32_e32 v234, 1, v230
	v_sub_u32_e32 v231, v231, v234
	v_lshrrev_b32_e32 v234, 3, v230
	v_lshl_add_u32 v231, v234, 15, v231
	v_lshlrev_b32_e32 v234, 16, v227
	v_sub_u32_e32 v234, v231, v234
	v_ashrrev_i32_e32 v235, 31, v234
	v_lshl_add_u64 v[228:229], v[228:229], 0, v[234:235]
	v_mov_b32_e32 v232, 0x40000
	v_mov_b32_e32 v233, 0
	ds_write_b16 v226, v69 offset:0
	v_lshlrev_b64 v[66:67], 15, v[82:83]
	v_cvt_pk_bf16_f32 v73, v63, s0
	v_lshl_add_u64 v[66:67], v[100:101], 0, v[66:67]
	v_mov_b32_e32 v77, v33
	ds_write_b16 v226, v73 offset:144
	v_lshlrev_b64 v[66:67], 15, v[76:77]
	v_lshl_add_u64 v[66:67], v[100:101], 0, v[66:67]
	v_mov_b32_e32 v73, v33
	ds_write_b16 v226, v68 offset:288
	v_lshlrev_b64 v[66:67], 15, v[72:73]
	v_cvt_pk_bf16_f32 v74, v65, s0
	v_lshl_add_u64 v[66:67], v[100:101], 0, v[66:67]
	s_mov_b64 s[22:23], 0
	ds_write_b16 v226, v74 offset:432

.LBB0_2416:
	v_or_b32_e32 v117, 16, v147
	v_or_b32_e32 v74, v71, v117
	v_mov_b32_e32 v75, v33
	v_cvt_pk_bf16_f32 v77, v58, s0
	v_cvt_pk_bf16_f32 v73, v60, s0
	s_mov_b64 s[22:23], -1
	s_and_b64 vcc, exec, s[40:41]
	v_add_u32_e32 v68, v71, v147
	v_lshlrev_b64 v[98:99], 15, v[74:75]
	v_or_b32_e32 v88, 1, v74
	v_or_b32_e32 v80, 2, v74
	v_or_b32_e32 v74, 3, v74
	s_cbranch_vccnz .LBB0_2418
	v_mov_b32_e32 v69, v33
	v_lshl_add_u64 v[78:79], v[68:69], 2, v[102:103]
	flat_store_dwordx4 v[78:79], v[58:61] offset:64
	v_lshl_add_u64 v[78:79], v[100:101], 0, v[98:99]
	v_mov_b32_e32 v89, v33
	ds_write_b16 v226, v77 offset:2304
	v_lshlrev_b64 v[78:79], 15, v[88:89]
	v_cvt_pk_bf16_f32 v67, v59, s0
	v_lshl_add_u64 v[78:79], v[100:101], 0, v[78:79]
	v_mov_b32_e32 v81, v33
	ds_write_b16 v226, v67 offset:2448
	v_lshlrev_b64 v[78:79], 15, v[80:81]
	v_lshl_add_u64 v[78:79], v[100:101], 0, v[78:79]
	v_mov_b32_e32 v75, v33
	ds_write_b16 v226, v73 offset:2592
	v_lshlrev_b64 v[78:79], 15, v[74:75]
	v_cvt_pk_bf16_f32 v67, v61, s0
	v_lshl_add_u64 v[78:79], v[100:101], 0, v[78:79]
	s_mov_b64 s[22:23], 0
	ds_write_b16 v226, v67 offset:2736

.LBB0_2420:
	v_or_b32_e32 v118, 32, v147
	v_or_b32_e32 v78, v71, v118
	v_mov_b32_e32 v79, v33
	v_cvt_pk_bf16_f32 v75, v54, s0
	v_cvt_pk_bf16_f32 v73, v56, s0
	s_mov_b64 s[22:23], -1
	s_and_b64 vcc, exec, s[40:41]
	v_lshlrev_b64 v[104:105], 15, v[78:79]
	v_or_b32_e32 v92, 1, v78
	v_or_b32_e32 v86, 2, v78
	v_or_b32_e32 v78, 3, v78
	s_cbranch_vccnz .LBB0_2422
	v_mov_b32_e32 v69, v33
	v_lshl_add_u64 v[84:85], v[68:69], 2, v[102:103]
	flat_store_dwordx4 v[84:85], v[54:57] offset:128
	v_lshl_add_u64 v[84:85], v[100:101], 0, v[104:105]
	v_mov_b32_e32 v93, v33
	ds_write_b16 v226, v75 offset:4608
	v_lshlrev_b64 v[84:85], 15, v[92:93]
	v_cvt_pk_bf16_f32 v67, v55, s0
	v_lshl_add_u64 v[84:85], v[100:101], 0, v[84:85]
	v_mov_b32_e32 v87, v33
	ds_write_b16 v226, v67 offset:4752
	v_lshlrev_b64 v[84:85], 15, v[86:87]
	v_lshl_add_u64 v[84:85], v[100:101], 0, v[84:85]
	v_mov_b32_e32 v79, v33
	ds_write_b16 v226, v73 offset:4896
	v_lshlrev_b64 v[84:85], 15, v[78:79]
	v_cvt_pk_bf16_f32 v67, v57, s0
	v_lshl_add_u64 v[84:85], v[100:101], 0, v[84:85]
	s_mov_b64 s[22:23], 0
	ds_write_b16 v226, v67 offset:5040

.LBB0_2424:
	v_or_b32_e32 v119, 48, v147
	v_or_b32_e32 v84, v71, v119
	v_mov_b32_e32 v85, v33
	v_cvt_pk_bf16_f32 v73, v50, s0
	v_cvt_pk_bf16_f32 v71, v52, s0
	s_mov_b64 s[22:23], -1
	s_and_b64 vcc, exec, s[40:41]
	v_lshlrev_b64 v[106:107], 15, v[84:85]
	v_or_b32_e32 v94, 1, v84
	v_or_b32_e32 v90, 2, v84
	v_or_b32_e32 v84, 3, v84
	s_cbranch_vccnz .LBB0_2426
	v_mov_b32_e32 v69, v33
	v_lshl_add_u64 v[102:103], v[68:69], 2, v[102:103]
	flat_store_dwordx4 v[102:103], v[50:53] offset:192
	v_lshl_add_u64 v[102:103], v[100:101], 0, v[106:107]
	v_mov_b32_e32 v95, v33
	ds_write_b16 v226, v73 offset:6912
	v_lshlrev_b64 v[102:103], 15, v[94:95]
	v_cvt_pk_bf16_f32 v67, v51, s0
	v_lshl_add_u64 v[102:103], v[100:101], 0, v[102:103]
	v_mov_b32_e32 v91, v33
	ds_write_b16 v226, v67 offset:7056
	v_lshlrev_b64 v[102:103], 15, v[90:91]
	v_lshl_add_u64 v[102:103], v[100:101], 0, v[102:103]
	v_mov_b32_e32 v85, v33
	ds_write_b16 v226, v71 offset:7200
	v_lshlrev_b64 v[102:103], 15, v[84:85]
	v_cvt_pk_bf16_f32 v67, v53, s0
	v_lshl_add_u64 v[100:101], v[100:101], 0, v[102:103]
	s_mov_b64 s[22:23], 0
	ds_write_b16 v226, v67 offset:7344

.LBB0_2428:
	v_or_b32_e32 v100, 16, v148
	v_ashrrev_i32_e32 v101, 31, v100
	v_lshl_add_u64 v[102:103], s[12:13], 0, v[100:101]
	s_movk_i32 s28, 0x600
	v_mad_u64_u32 v[108:109], s[22:23], v102, s28, 0
	v_mad_i32_i24 v109, v103, s28, v109
	v_cvt_pk_bf16_f32 v71, v46, s0
	v_cvt_pk_bf16_f32 v69, v48, s0
	s_mov_b64 s[22:23], -1
	s_and_b64 vcc, exec, s[40:41]
	v_lshl_add_u64 v[110:111], s[56:57], 0, v[108:109]
	v_lshlrev_b64 v[108:109], 1, v[100:101]
	v_lshl_add_u64 v[102:103], s[16:17], 0, v[96:97]
	s_cbranch_vccnz .LBB0_2430
	v_lshl_add_u64 v[96:97], v[32:33], 2, v[110:111]
	flat_store_dwordx4 v[96:97], v[46:49]
	v_lshl_add_u64 v[96:97], v[102:103], 0, v[108:109]
	v_mov_b32_e32 v83, v33
	ds_write_b16 v226, v71 offset:32
	v_lshlrev_b64 v[96:97], 15, v[82:83]
	v_lshl_add_u64 v[96:97], s[16:17], 0, v[96:97]
	v_cvt_pk_bf16_f32 v67, v47, s0
	v_lshl_add_u64 v[96:97], v[96:97], 0, v[108:109]
	v_mov_b32_e32 v77, v33
	ds_write_b16 v226, v67 offset:176
	v_lshlrev_b64 v[96:97], 15, v[76:77]
	v_lshl_add_u64 v[96:97], s[16:17], 0, v[96:97]
	v_lshl_add_u64 v[96:97], v[96:97], 0, v[108:109]
	v_mov_b32_e32 v73, v33
	ds_write_b16 v226, v69 offset:320
	v_lshlrev_b64 v[96:97], 15, v[72:73]
	v_lshl_add_u64 v[96:97], s[16:17], 0, v[96:97]
	v_cvt_pk_bf16_f32 v67, v49, s0
	v_lshl_add_u64 v[96:97], v[96:97], 0, v[108:109]
	s_mov_b64 s[22:23], 0
	ds_write_b16 v226, v67 offset:464

.LBB0_2432:
	v_cvt_pk_bf16_f32 v73, v42, s0
	v_cvt_pk_bf16_f32 v71, v44, s0
	s_mov_b64 s[22:23], -1
	s_and_b64 vcc, exec, s[40:41]
	v_lshl_add_u64 v[100:101], s[16:17], 0, v[98:99]
	s_cbranch_vccnz .LBB0_2434
	v_mov_b32_e32 v69, v33
	v_lshl_add_u64 v[96:97], v[68:69], 2, v[110:111]
	flat_store_dwordx4 v[96:97], v[42:45] offset:64
	v_lshl_add_u64 v[96:97], v[100:101], 0, v[108:109]
	v_mov_b32_e32 v89, v33
	ds_write_b16 v226, v73 offset:2336
	v_lshlrev_b64 v[96:97], 15, v[88:89]
	v_lshl_add_u64 v[96:97], s[16:17], 0, v[96:97]
	v_cvt_pk_bf16_f32 v67, v43, s0
	v_lshl_add_u64 v[96:97], v[96:97], 0, v[108:109]
	v_mov_b32_e32 v81, v33
	ds_write_b16 v226, v67 offset:2480
	v_lshlrev_b64 v[96:97], 15, v[80:81]
	v_lshl_add_u64 v[96:97], s[16:17], 0, v[96:97]
	v_lshl_add_u64 v[96:97], v[96:97], 0, v[108:109]
	v_mov_b32_e32 v75, v33
	ds_write_b16 v226, v71 offset:2624
	v_lshlrev_b64 v[96:97], 15, v[74:75]
	v_lshl_add_u64 v[96:97], s[16:17], 0, v[96:97]
	v_cvt_pk_bf16_f32 v67, v45, s0
	v_lshl_add_u64 v[96:97], v[96:97], 0, v[108:109]
	s_mov_b64 s[22:23], 0
	ds_write_b16 v226, v67 offset:2768

.LBB0_2436:
	v_cvt_pk_bf16_f32 v73, v38, s0
	v_cvt_pk_bf16_f32 v71, v40, s0
	s_mov_b64 s[22:23], -1
	s_and_b64 vcc, exec, s[40:41]
	v_lshl_add_u64 v[98:99], s[16:17], 0, v[104:105]
	s_cbranch_vccnz .LBB0_2438
	v_mov_b32_e32 v69, v33
	v_lshl_add_u64 v[96:97], v[68:69], 2, v[110:111]
	flat_store_dwordx4 v[96:97], v[38:41] offset:128
	v_lshl_add_u64 v[96:97], v[98:99], 0, v[108:109]
	v_mov_b32_e32 v93, v33
	ds_write_b16 v226, v73 offset:4640
	v_lshlrev_b64 v[96:97], 15, v[92:93]
	v_lshl_add_u64 v[96:97], s[16:17], 0, v[96:97]
	v_cvt_pk_bf16_f32 v67, v39, s0
	v_lshl_add_u64 v[96:97], v[96:97], 0, v[108:109]
	v_mov_b32_e32 v87, v33
	ds_write_b16 v226, v67 offset:4784
	v_lshlrev_b64 v[96:97], 15, v[86:87]
	v_lshl_add_u64 v[96:97], s[16:17], 0, v[96:97]
	v_lshl_add_u64 v[96:97], v[96:97], 0, v[108:109]
	v_mov_b32_e32 v79, v33
	ds_write_b16 v226, v71 offset:4928
	v_lshlrev_b64 v[96:97], 15, v[78:79]
	v_lshl_add_u64 v[96:97], s[16:17], 0, v[96:97]
	v_cvt_pk_bf16_f32 v67, v41, s0
	v_lshl_add_u64 v[96:97], v[96:97], 0, v[108:109]
	s_mov_b64 s[22:23], 0
	ds_write_b16 v226, v67 offset:5072

.LBB0_2440:
	v_cvt_pk_bf16_f32 v73, v34, s0
	v_cvt_pk_bf16_f32 v71, v36, s0
	s_mov_b64 s[22:23], -1
	s_and_b64 vcc, exec, s[40:41]
	v_lshl_add_u64 v[96:97], s[16:17], 0, v[106:107]
	s_cbranch_vccnz .LBB0_2442
	v_mov_b32_e32 v69, v33
	v_lshl_add_u64 v[104:105], v[68:69], 2, v[110:111]
	flat_store_dwordx4 v[104:105], v[34:37] offset:192
	v_lshl_add_u64 v[104:105], v[96:97], 0, v[108:109]
	v_mov_b32_e32 v95, v33
	ds_write_b16 v226, v73 offset:6944
	v_lshlrev_b64 v[104:105], 15, v[94:95]
	v_lshl_add_u64 v[104:105], s[16:17], 0, v[104:105]
	v_cvt_pk_bf16_f32 v67, v35, s0
	v_lshl_add_u64 v[104:105], v[104:105], 0, v[108:109]
	v_mov_b32_e32 v91, v33
	ds_write_b16 v226, v67 offset:7088
	v_lshlrev_b64 v[104:105], 15, v[90:91]
	v_lshl_add_u64 v[104:105], s[16:17], 0, v[104:105]
	v_lshl_add_u64 v[104:105], v[104:105], 0, v[108:109]
	v_mov_b32_e32 v85, v33
	ds_write_b16 v226, v71 offset:7232
	v_lshlrev_b64 v[104:105], 15, v[84:85]
	v_lshl_add_u64 v[104:105], s[16:17], 0, v[104:105]
	v_cvt_pk_bf16_f32 v67, v37, s0
	v_lshl_add_u64 v[104:105], v[104:105], 0, v[108:109]
	s_mov_b64 s[22:23], 0
	ds_write_b16 v226, v67 offset:7376

.LBB0_2444:
	v_or_b32_e32 v104, 32, v148
	v_ashrrev_i32_e32 v105, 31, v104
	v_lshl_add_u64 v[106:107], s[12:13], 0, v[104:105]
	s_movk_i32 s28, 0x600
	v_mad_u64_u32 v[108:109], s[22:23], v106, s28, 0
	v_mad_i32_i24 v109, v107, s28, v109
	v_cvt_pk_bf16_f32 v71, v28, s0
	v_cvt_pk_bf16_f32 v69, v30, s0
	s_mov_b64 s[22:23], -1
	s_and_b64 vcc, exec, s[40:41]
	v_lshl_add_u64 v[106:107], s[56:57], 0, v[108:109]
	v_lshlrev_b64 v[104:105], 1, v[104:105]
	s_cbranch_vccnz .LBB0_2446
	v_lshl_add_u64 v[108:109], v[32:33], 2, v[106:107]
	flat_store_dwordx4 v[108:109], v[28:31]
	v_lshl_add_u64 v[108:109], v[102:103], 0, v[104:105]
	v_mov_b32_e32 v83, v33
	ds_write_b16 v226, v71 offset:64
	v_lshlrev_b64 v[108:109], 15, v[82:83]
	v_lshl_add_u64 v[108:109], s[16:17], 0, v[108:109]
	v_cvt_pk_bf16_f32 v67, v29, s0
	v_lshl_add_u64 v[108:109], v[108:109], 0, v[104:105]
	v_mov_b32_e32 v77, v33
	ds_write_b16 v226, v67 offset:208
	v_lshlrev_b64 v[108:109], 15, v[76:77]
	v_lshl_add_u64 v[108:109], s[16:17], 0, v[108:109]
	v_lshl_add_u64 v[108:109], v[108:109], 0, v[104:105]
	v_mov_b32_e32 v73, v33
	ds_write_b16 v226, v69 offset:352
	v_lshlrev_b64 v[108:109], 15, v[72:73]
	v_lshl_add_u64 v[108:109], s[16:17], 0, v[108:109]
	v_cvt_pk_bf16_f32 v67, v31, s0
	v_lshl_add_u64 v[108:109], v[108:109], 0, v[104:105]
	s_mov_b64 s[22:23], 0
	ds_write_b16 v226, v67 offset:496

.LBB0_2448:
	v_cvt_pk_bf16_f32 v73, v24, s0
	v_cvt_pk_bf16_f32 v71, v26, s0
	s_and_b64 vcc, exec, s[40:41]
	s_mov_b64 s[22:23], -1
	s_cbranch_vccnz .LBB0_2450
	v_mov_b32_e32 v69, v33
	v_lshl_add_u64 v[112:113], v[68:69], 2, v[106:107]
	flat_store_dwordx4 v[112:113], v[24:27] offset:64
	v_lshl_add_u64 v[112:113], v[100:101], 0, v[104:105]
	v_mov_b32_e32 v89, v33
	ds_write_b16 v226, v73 offset:2368
	v_lshlrev_b64 v[112:113], 15, v[88:89]
	v_lshl_add_u64 v[112:113], s[16:17], 0, v[112:113]
	v_cvt_pk_bf16_f32 v67, v25, s0
	v_lshl_add_u64 v[112:113], v[112:113], 0, v[104:105]
	v_mov_b32_e32 v81, v33
	ds_write_b16 v226, v67 offset:2512
	v_lshlrev_b64 v[112:113], 15, v[80:81]
	v_lshl_add_u64 v[112:113], s[16:17], 0, v[112:113]
	v_lshl_add_u64 v[112:113], v[112:113], 0, v[104:105]
	v_mov_b32_e32 v75, v33
	ds_write_b16 v226, v71 offset:2656
	v_lshlrev_b64 v[112:113], 15, v[74:75]
	v_lshl_add_u64 v[112:113], s[16:17], 0, v[112:113]
	v_cvt_pk_bf16_f32 v67, v27, s0
	v_lshl_add_u64 v[112:113], v[112:113], 0, v[104:105]
	s_mov_b64 s[22:23], 0
	ds_write_b16 v226, v67 offset:2800

.LBB0_2452:
	v_cvt_pk_bf16_f32 v73, v20, s0
	v_cvt_pk_bf16_f32 v71, v22, s0
	s_and_b64 vcc, exec, s[40:41]
	s_mov_b64 s[22:23], -1
	s_cbranch_vccnz .LBB0_2454
	v_mov_b32_e32 v69, v33
	v_lshl_add_u64 v[112:113], v[68:69], 2, v[106:107]
	flat_store_dwordx4 v[112:113], v[20:23] offset:128
	v_lshl_add_u64 v[112:113], v[98:99], 0, v[104:105]
	v_mov_b32_e32 v93, v33
	ds_write_b16 v226, v73 offset:4672
	v_lshlrev_b64 v[112:113], 15, v[92:93]
	v_lshl_add_u64 v[112:113], s[16:17], 0, v[112:113]
	v_cvt_pk_bf16_f32 v67, v21, s0
	v_lshl_add_u64 v[112:113], v[112:113], 0, v[104:105]
	v_mov_b32_e32 v87, v33
	ds_write_b16 v226, v67 offset:4816
	v_lshlrev_b64 v[112:113], 15, v[86:87]
	v_lshl_add_u64 v[112:113], s[16:17], 0, v[112:113]
	v_lshl_add_u64 v[112:113], v[112:113], 0, v[104:105]
	v_mov_b32_e32 v79, v33
	ds_write_b16 v226, v71 offset:4960
	v_lshlrev_b64 v[112:113], 15, v[78:79]
	v_lshl_add_u64 v[112:113], s[16:17], 0, v[112:113]
	v_cvt_pk_bf16_f32 v67, v23, s0
	v_lshl_add_u64 v[112:113], v[112:113], 0, v[104:105]
	s_mov_b64 s[22:23], 0
	ds_write_b16 v226, v67 offset:5104

.LBB0_2456:
	v_cvt_pk_bf16_f32 v73, v16, s0
	v_cvt_pk_bf16_f32 v71, v18, s0
	s_and_b64 vcc, exec, s[40:41]
	s_mov_b64 s[22:23], -1
	s_cbranch_vccnz .LBB0_2458
	v_mov_b32_e32 v69, v33
	v_lshl_add_u64 v[106:107], v[68:69], 2, v[106:107]
	flat_store_dwordx4 v[106:107], v[16:19] offset:192
	v_lshl_add_u64 v[106:107], v[96:97], 0, v[104:105]
	v_mov_b32_e32 v95, v33
	ds_write_b16 v226, v73 offset:6976
	v_lshlrev_b64 v[106:107], 15, v[94:95]
	v_lshl_add_u64 v[106:107], s[16:17], 0, v[106:107]
	v_cvt_pk_bf16_f32 v67, v17, s0
	v_lshl_add_u64 v[106:107], v[106:107], 0, v[104:105]
	v_mov_b32_e32 v91, v33
	ds_write_b16 v226, v67 offset:7120
	v_lshlrev_b64 v[106:107], 15, v[90:91]
	v_lshl_add_u64 v[106:107], s[16:17], 0, v[106:107]
	v_lshl_add_u64 v[106:107], v[106:107], 0, v[104:105]
	v_mov_b32_e32 v85, v33
	ds_write_b16 v226, v71 offset:7264
	v_lshlrev_b64 v[106:107], 15, v[84:85]
	v_lshl_add_u64 v[106:107], s[16:17], 0, v[106:107]
	v_cvt_pk_bf16_f32 v67, v19, s0
	v_lshl_add_u64 v[104:105], v[106:107], 0, v[104:105]
	s_mov_b64 s[22:23], 0
	ds_write_b16 v226, v67 offset:7408

.LBB0_2460:
	v_or_b32_e32 v104, 48, v148
	v_ashrrev_i32_e32 v105, 31, v104
	v_lshl_add_u64 v[106:107], s[12:13], 0, v[104:105]
	s_movk_i32 s28, 0x600
	v_mad_u64_u32 v[108:109], s[22:23], v106, s28, 0
	v_mad_i32_i24 v109, v107, s28, v109
	v_cvt_pk_bf16_f32 v75, v12, s0
	v_cvt_pk_bf16_f32 v69, v14, s0
	s_mov_b64 s[22:23], -1
	s_and_b64 vcc, exec, s[40:41]
	v_lshl_add_u64 v[106:107], s[56:57], 0, v[108:109]
	v_lshlrev_b64 v[104:105], 1, v[104:105]
	s_cbranch_vccnz .LBB0_2462
	v_mov_b32_e32 v83, v33
	v_lshlrev_b64 v[82:83], 15, v[82:83]
	v_mov_b32_e32 v77, v33
	v_mov_b32_e32 v73, v33
	v_lshl_add_u64 v[82:83], s[16:17], 0, v[82:83]
	v_lshlrev_b64 v[76:77], 15, v[76:77]
	v_lshlrev_b64 v[72:73], 15, v[72:73]
	v_lshl_add_u64 v[108:109], v[32:33], 2, v[106:107]
	v_lshl_add_u64 v[102:103], v[102:103], 0, v[104:105]
	v_cvt_pk_bf16_f32 v67, v13, s0
	v_lshl_add_u64 v[82:83], v[82:83], 0, v[104:105]
	v_lshl_add_u64 v[76:77], s[16:17], 0, v[76:77]
	v_lshl_add_u64 v[72:73], s[16:17], 0, v[72:73]
	flat_store_dwordx4 v[108:109], v[12:15]
	ds_write_b16 v226, v75 offset:96
	ds_write_b16 v226, v67 offset:240
	v_lshl_add_u64 v[76:77], v[76:77], 0, v[104:105]
	v_cvt_pk_bf16_f32 v67, v15, s0
	v_lshl_add_u64 v[72:73], v[72:73], 0, v[104:105]
	s_mov_b64 s[22:23], 0
	ds_write_b16 v226, v69 offset:384
	ds_write_b16 v226, v67 offset:528

.LBB0_2464:
	v_cvt_pk_bf16_f32 v76, v8, s0
	v_cvt_pk_bf16_f32 v32, v10, s0
	s_and_b64 vcc, exec, s[40:41]
	s_mov_b64 s[22:23], -1
	s_cbranch_vccnz .LBB0_2466
	v_mov_b32_e32 v69, v33
	v_lshl_add_u64 v[82:83], v[68:69], 2, v[106:107]
	flat_store_dwordx4 v[82:83], v[8:11] offset:64
	v_lshl_add_u64 v[82:83], v[100:101], 0, v[104:105]
	v_mov_b32_e32 v89, v33
	ds_write_b16 v226, v76 offset:2400
	v_lshlrev_b64 v[82:83], 15, v[88:89]
	v_mov_b32_e32 v81, v33
	v_mov_b32_e32 v75, v33
	v_lshl_add_u64 v[82:83], s[16:17], 0, v[82:83]
	v_lshlrev_b64 v[80:81], 15, v[80:81]
	v_lshlrev_b64 v[74:75], 15, v[74:75]
	v_cvt_pk_bf16_f32 v67, v9, s0
	v_lshl_add_u64 v[82:83], v[82:83], 0, v[104:105]
	v_lshl_add_u64 v[80:81], s[16:17], 0, v[80:81]
	v_lshl_add_u64 v[74:75], s[16:17], 0, v[74:75]
	ds_write_b16 v226, v67 offset:2544
	v_lshl_add_u64 v[80:81], v[80:81], 0, v[104:105]
	v_cvt_pk_bf16_f32 v67, v11, s0
	v_lshl_add_u64 v[74:75], v[74:75], 0, v[104:105]
	s_mov_b64 s[22:23], 0
	ds_write_b16 v226, v32 offset:2688
	ds_write_b16 v226, v67 offset:2832

.LBB0_2468:
	v_cvt_pk_bf16_f32 v74, v4, s0
	v_cvt_pk_bf16_f32 v32, v6, s0
	s_and_b64 vcc, exec, s[40:41]
	s_mov_b64 s[22:23], -1
	s_cbranch_vccnz .LBB0_2470
	v_mov_b32_e32 v69, v33
	v_lshl_add_u64 v[76:77], v[68:69], 2, v[106:107]
	flat_store_dwordx4 v[76:77], v[4:7] offset:128
	v_lshl_add_u64 v[76:77], v[98:99], 0, v[104:105]
	v_mov_b32_e32 v93, v33
	ds_write_b16 v226, v74 offset:4704
	v_lshlrev_b64 v[76:77], 15, v[92:93]
	v_lshl_add_u64 v[76:77], s[16:17], 0, v[76:77]
	v_cvt_pk_bf16_f32 v67, v5, s0
	v_lshl_add_u64 v[76:77], v[76:77], 0, v[104:105]
	v_mov_b32_e32 v87, v33
	ds_write_b16 v226, v67 offset:4848
	v_lshlrev_b64 v[76:77], 15, v[86:87]
	v_lshl_add_u64 v[76:77], s[16:17], 0, v[76:77]
	v_lshl_add_u64 v[76:77], v[76:77], 0, v[104:105]
	v_mov_b32_e32 v79, v33
	ds_write_b16 v226, v32 offset:4992
	v_lshlrev_b64 v[76:77], 15, v[78:79]
	v_lshl_add_u64 v[76:77], s[16:17], 0, v[76:77]
	v_cvt_pk_bf16_f32 v67, v7, s0
	v_lshl_add_u64 v[76:77], v[76:77], 0, v[104:105]
	s_mov_b64 s[22:23], 0
	ds_write_b16 v226, v67 offset:5136

.LBB0_2472:
	v_cvt_pk_bf16_f32 v74, v0, s0
	v_cvt_pk_bf16_f32 v32, v2, s0
	s_and_b64 vcc, exec, s[40:41]
	s_mov_b64 s[22:23], -1
	s_cbranch_vccnz .LBB0_2474
	v_mov_b32_e32 v69, v33
	v_lshl_add_u64 v[76:77], v[68:69], 2, v[106:107]
	flat_store_dwordx4 v[76:77], v[0:3] offset:192
	v_lshl_add_u64 v[76:77], v[96:97], 0, v[104:105]
	v_mov_b32_e32 v95, v33
	ds_write_b16 v226, v74 offset:7008
	v_lshlrev_b64 v[76:77], 15, v[94:95]
	v_lshl_add_u64 v[76:77], s[16:17], 0, v[76:77]
	v_cvt_pk_bf16_f32 v67, v1, s0
	v_lshl_add_u64 v[76:77], v[76:77], 0, v[104:105]
	v_mov_b32_e32 v91, v33
	ds_write_b16 v226, v67 offset:7152
	v_lshlrev_b64 v[76:77], 15, v[90:91]
	v_lshl_add_u64 v[76:77], s[16:17], 0, v[76:77]
	v_lshl_add_u64 v[76:77], v[76:77], 0, v[104:105]
	v_mov_b32_e32 v85, v33
	ds_write_b16 v226, v32 offset:7296
	v_lshlrev_b64 v[76:77], 15, v[84:85]
	v_lshl_add_u64 v[76:77], s[16:17], 0, v[76:77]
	v_cvt_pk_bf16_f32 v67, v3, s0
	v_lshl_add_u64 v[76:77], v[76:77], 0, v[104:105]
	s_mov_b64 s[22:23], 0
	ds_write_b16 v226, v67 offset:7440
